# hoist loop-invariant gain/conv-weight/param loads out of norm, norm_in, final_norm, rwkv_pre, rwkv_post loops (removes per-store serialized waits)
# speedup vs baseline: 1.0067x; 1.0047x over previous
; __device__ __forceinline__ unsigned pk2(float lo, float hi) { return cvt_pk_bf16(lo, hi); }
; __device__ __forceinline__ void phase_norm_in(const Frame& F, const float* xp, const float* xs, const float* gain, bf16* xn, bf16* xb) {
;     for (int m = F.gw; m < T; m += F.NGW) {
;         const float* src_row = m < 8192 ? xp + (size_t)m * D : xs + (size_t)(m - 8192) * D;
;         const f32x4* xr = (const f32x4*)src_row + F.lane; const f32x4* gr = (const f32x4*)gain + F.lane;
;         f32x4 v[8]; float s = 0.f;
; #pragma unroll
;         for (int j = 0; j < 8; ++j) { v[j] = xr[64 * j]; s += (v[j].x * v[j].x + v[j].y * v[j].y) + (v[j].z * v[j].z + v[j].w * v[j].w); }
;         const float rstd = 1.0f / sqrtf(wave_sum(s) * (1.0f / D) + 1e-6f);
;         v2u* o8 = (v2u*)(xn + (size_t)m * D) + F.lane; v2u* b8 = (v2u*)(xb + (size_t)m * D) + F.lane;
; #pragma unroll
;         for (int j = 0; j < 8; ++j) { const f32x4 g = gr[64 * j]; v2u w; w.x = pk2(v[j].x * rstd * g.x, v[j].y * rstd * g.y); w.y = pk2(v[j].z * rstd * g.z, v[j].w * rstd * g.w); o8[64 * j] = w;
;             v2u b; b.x = pk2(v[j].x, v[j].y); b.y = pk2(v[j].z, v[j].w); b8[64 * j] = b; }
;     }
; }
.LBB0_87:
	s_or_b64 exec, exec, s[4:5]
	v_readlane_b32 s4, v254, 18
	v_readlane_b32 s5, v254, 19
	s_andn2_b64 vcc, exec, s[4:5]
	s_cbranch_vccnz .LBB0_93
	s_cmp_gt_i32 s10, 0x9fff
	s_cbranch_scc1 .LBB0_93
	s_load_dwordx2 s[20:21], s[18:19], 0x10
	s_load_dwordx4 s[4:7], s[18:19], 0x0
	v_lshlrev_b32_e32 v184, 4, v6
	s_ashr_i32 s11, s10, 31
	s_ashr_i32 s13, s12, 31
	s_waitcnt vmcnt(0) lgkmcnt(0)
	v_lshl_add_u64 v[32:33], s[20:21], 0, v[184:185]
	v_lshlrev_b32_e32 v184, 3, v6
	v_lshl_add_u64 v[0:1], s[14:15], 0, v[184:185]
	s_mov_b64 s[14:15], 0xd600000
	v_lshl_add_u64 v[2:3], s[16:17], 0, v[184:185]
	v_lshl_add_u64 v[34:35], v[0:1], 0, s[14:15]
	s_mov_b64 s[14:15], 0xa000000
	v_lshl_add_u64 v[36:37], v[2:3], 0, s[14:15]
	s_mov_b64 s[14:15], 0x1000
	v_lshl_add_u64 v[38:39], v[32:33], 0, s[14:15]
	s_mov_b64 s[14:15], 0x1400
	v_lshl_add_u64 v[40:41], v[32:33], 0, s[14:15]
	s_mov_b64 s[14:15], 0x1800
	v_lshl_add_u64 v[42:43], v[32:33], 0, s[14:15]
	s_mov_b64 s[14:15], 0x1c00
	v_lshl_add_u64 v[44:45], v[32:33], 0, s[14:15]
	s_lshl_b64 s[14:15], s[10:11], 13
	s_add_u32 s14, s4, s14
	s_addc_u32 s15, s5, s15
	s_lshl_b64 s[16:17], s[12:13], 13
	v_lshlrev_b32_e32 v184, 4, v6
	global_load_dwordx4 v[96:99], v[32:33], off
	global_load_dwordx4 v[100:103], v[32:33], off offset:1024
	global_load_dwordx4 v[104:107], v[32:33], off offset:2048
	global_load_dwordx4 v[108:111], v[32:33], off offset:3072
	global_load_dwordx4 v[112:115], v[38:39], off
	global_load_dwordx4 v[116:119], v[40:41], off
	global_load_dwordx4 v[120:123], v[42:43], off
	global_load_dwordx4 v[124:127], v[44:45], off
	s_branch .LBB0_91
.LBB0_90:
	global_load_dwordx4 v[28:31], v184, s[18:19]
	global_load_dwordx4 v[24:27], v184, s[18:19] offset:1024
	global_load_dwordx4 v[20:23], v184, s[18:19] offset:2048
	global_load_dwordx4 v[16:19], v184, s[18:19] offset:3072
	v_lshl_add_u64 v[0:1], s[18:19], 0, v[184:185]
	v_add_co_u32_e32 v4, vcc, s33, v0
	s_lshl_b64 s[4:5], s[4:5], 12
	s_nop 0
	v_addc_co_u32_e32 v5, vcc, 0, v1, vcc
	global_load_dwordx4 v[8:11], v[4:5], off
	global_load_dwordx4 v[12:15], v[4:5], off offset:1024
	global_load_dwordx4 v[0:3], v[4:5], off offset:3072
	s_nop 0
	global_load_dwordx4 v[4:7], v[4:5], off offset:2048
	v_mbcnt_lo_u32_b32 v50, -1, 0
	v_mbcnt_hi_u32_b32 v50, -1, v50
	v_mbcnt_lo_u32_b32 v68, -1, 0
	v_mbcnt_hi_u32_b32 v68, -1, v68
	v_mbcnt_lo_u32_b32 v69, -1, 0
	v_mbcnt_hi_u32_b32 v69, -1, v69
	v_mbcnt_lo_u32_b32 v70, -1, 0
	v_mbcnt_hi_u32_b32 v70, -1, v70
	v_mbcnt_lo_u32_b32 v71, -1, 0
	v_mbcnt_hi_u32_b32 v71, -1, v71
	v_mbcnt_lo_u32_b32 v72, -1, 0
	v_mbcnt_hi_u32_b32 v72, -1, v72
	v_lshlrev_b32_e32 v50, 2, v50
	v_xor_b32_e32 v73, 4, v50
	s_add_u32 s10, s10, s12
	s_addc_u32 s11, s11, s13
	s_add_u32 s14, s14, s16
	s_addc_u32 s15, s15, s17
	s_cmp_lt_i32 s10, 0xa000
	s_waitcnt vmcnt(7)
	v_mov_b32_e32 v52, v29
	s_waitcnt vmcnt(6)
	v_mov_b32_e32 v53, v25
	v_mov_b32_e32 v56, v31
	v_mov_b32_e32 v57, v27
	v_mov_b32_e32 v50, v28
	v_mov_b32_e32 v51, v24
	v_mov_b32_e32 v54, v30
	v_mov_b32_e32 v55, v26
	s_waitcnt vmcnt(5)
	v_pk_mul_f32 v[58:59], v[22:23], v[22:23]
	v_pk_mul_f32 v[60:61], v[20:21], v[20:21]
	v_pk_mul_f32 v[52:53], v[52:53], v[52:53]
	v_pk_mul_f32 v[56:57], v[56:57], v[56:57]
	v_pk_mov_b32 v[66:67], v[60:61], v[58:59] op_sel:[1,0]
	v_mov_b32_e32 v61, v59
	v_pk_fma_f32 v[50:51], v[50:51], v[50:51], v[52:53]
	v_pk_fma_f32 v[52:53], v[54:55], v[54:55], v[56:57]
	s_waitcnt vmcnt(4)
	v_mul_f32_e32 v62, v17, v17
	v_mul_f32_e32 v64, v19, v19
	v_pk_add_f32 v[54:55], v[66:67], v[60:61]
	v_pk_add_f32 v[50:51], v[50:51], v[52:53]
	v_pk_fma_f32 v[58:59], v[16:17], v[16:17], v[62:63] op_sel_hi:[1,1,0]
	v_pk_fma_f32 v[62:63], v[18:19], v[18:19], v[64:65] op_sel_hi:[1,1,0]
	s_waitcnt vmcnt(3)
	v_mul_f32_e32 v67, v8, v8
	v_mul_f32_e32 v74, v9, v9
	v_pk_add_f32 v[52:53], v[54:55], v[54:55] op_sel:[0,1] op_sel_hi:[1,0]
	v_pk_add_f32 v[50:51], v[50:51], v[50:51] op_sel:[0,1] op_sel_hi:[1,0]
	v_mul_f32_e32 v59, v10, v10
	v_mul_f32_e32 v63, v11, v11
	s_waitcnt vmcnt(2)
	v_pk_mul_f32 v[56:57], v[14:15], v[14:15]
	v_pk_mul_f32 v[60:61], v[12:13], v[12:13]
	v_mov_b32_e32 v53, v74
	v_mov_b32_e32 v51, v67
	v_pk_mov_b32 v[54:55], v[60:61], v[56:57] op_sel:[1,0]
	v_mov_b32_e32 v61, v57
	v_pk_add_f32 v[58:59], v[58:59], v[62:63]
	v_pk_add_f32 v[50:51], v[50:51], v[52:53]
	s_waitcnt vmcnt(0)
	v_mul_f32_e32 v64, v5, v5
	v_mul_f32_e32 v66, v7, v7
	v_pk_add_f32 v[54:55], v[54:55], v[60:61]
	v_pk_add_f32 v[50:51], v[50:51], v[58:59]
	v_mul_f32_e32 v75, v0, v0
	v_mul_f32_e32 v76, v1, v1
	v_mul_f32_e32 v77, v2, v2
	v_mul_f32_e32 v78, v3, v3
	v_pk_fma_f32 v[56:57], v[4:5], v[4:5], v[64:65] op_sel_hi:[1,1,0]
	v_pk_fma_f32 v[64:65], v[6:7], v[6:7], v[66:67] op_sel_hi:[1,1,0]
	v_pk_add_f32 v[54:55], v[54:55], v[54:55] op_sel:[0,1] op_sel_hi:[1,0]
	v_pk_add_f32 v[50:51], v[50:51], v[50:51] op_sel:[0,1] op_sel_hi:[1,0]
	v_mov_b32_e32 v57, v77
	v_mov_b32_e32 v65, v78
	v_mov_b32_e32 v55, v76
	v_mov_b32_e32 v51, v75
	v_pk_add_f32 v[56:57], v[56:57], v[64:65]
	v_pk_add_f32 v[50:51], v[50:51], v[54:55]
	v_lshlrev_b32_e32 v52, 2, v68
	v_pk_add_f32 v[50:51], v[50:51], v[56:57]
	v_xor_b32_e32 v52, 8, v52
	v_add_f32_e32 v50, v50, v51
	ds_bpermute_b32 v51, v73, v50
	v_cvt_pk_bf16_f32 v54, v28, v29
	s_waitcnt lgkmcnt(0)
	v_add_f32_e32 v50, v50, v51
	ds_bpermute_b32 v51, v52, v50
	v_lshlrev_b32_e32 v52, 2, v69
	v_xor_b32_e32 v52, 16, v52
	s_waitcnt lgkmcnt(0)
	v_add_f32_e32 v50, v50, v51
	ds_bpermute_b32 v51, v52, v50
	v_lshlrev_b32_e32 v52, 2, v70
	v_xor_b32_e32 v52, 32, v52
	s_waitcnt lgkmcnt(0)
	v_add_f32_e32 v50, v50, v51
	ds_bpermute_b32 v51, v52, v50
	v_lshlrev_b32_e32 v52, 2, v71
	v_xor_b32_e32 v52, 64, v52
	s_waitcnt lgkmcnt(0)
; __device__ __forceinline__ unsigned pk2(float lo, float hi) { return cvt_pk_bf16(lo, hi); }
; __device__ __forceinline__ void phase_norm_in(const Frame& F, const float* xp, const float* xs, const float* gain, bf16* xn, bf16* xb) {
;     ...
;         const float rstd = 1.0f / sqrtf(wave_sum(s) * (1.0f / D) + 1e-6f);
;         v2u* o8 = (v2u*)(xn + (size_t)m * D) + F.lane; v2u* b8 = (v2u*)(xb + (size_t)m * D) + F.lane;
; #pragma unroll
;         for (int j = 0; j < 8; ++j) { const f32x4 g = gr[64 * j]; v2u w; w.x = pk2(v[j].x * rstd * g.x, v[j].y * rstd * g.y); w.y = pk2(v[j].z * rstd * g.z, v[j].w * rstd * g.w); o8[64 * j] = w;
;             v2u b; b.x = pk2(v[j].x, v[j].y); b.y = pk2(v[j].z, v[j].w); b8[64 * j] = b; }
;     }
	v_add_f32_e32 v50, v50, v51
	ds_bpermute_b32 v51, v52, v50
	v_lshlrev_b32_e32 v52, 2, v72
	v_xor_b32_e32 v52, 0x80, v52
	s_waitcnt lgkmcnt(0)
	v_add_f32_e32 v50, v50, v51
	ds_bpermute_b32 v51, v52, v50
	v_lshl_add_u64 v[52:53], v[36:37], 0, s[4:5]
	s_waitcnt lgkmcnt(0)
	v_add_f32_e32 v50, v50, v51
	v_fmamk_f32 v50, v50, 0x3a000000, v208
	v_mul_f32_e32 v51, 0x4f800000, v50
	v_cmp_gt_f32_e32 vcc, s86, v50
	s_nop 1
	v_cndmask_b32_e32 v55, v50, v51, vcc
	v_sqrt_f32_e32 v56, v55
	v_lshl_add_u64 v[50:51], v[34:35], 0, s[4:5]
	v_add_u32_e32 v57, -1, v56
	v_add_u32_e32 v58, 1, v56
	v_fma_f32 v59, -v57, v56, v55
	v_fma_f32 v60, -v58, v56, v55
	v_cmp_ge_f32_e64 s[4:5], 0, v59
	s_nop 1
	v_cndmask_b32_e64 v56, v56, v57, s[4:5]
	v_cmp_lt_f32_e64 s[4:5], 0, v60
	s_nop 1
	v_cndmask_b32_e64 v56, v56, v58, s[4:5]
	v_mul_f32_e32 v57, 0x37800000, v56
	v_cndmask_b32_e32 v56, v56, v57, vcc
	v_cmp_class_f32_e32 vcc, v55, v204
	s_nop 1
	v_cndmask_b32_e32 v56, v56, v55, vcc
	v_div_scale_f32 v57, s[4:5], v56, v56, 1.0
	v_rcp_f32_e32 v58, v57
	v_div_scale_f32 v59, vcc, 1.0, v56, 1.0
	v_cvt_pk_bf16_f32 v55, v30, v31
	v_fma_f32 v60, -v57, v58, 1.0
	v_fmac_f32_e32 v58, v60, v58
	v_mul_f32_e32 v60, v59, v58
	v_fma_f32 v61, -v57, v60, v59
	v_fmac_f32_e32 v60, v61, v58
	v_fma_f32 v57, -v57, v60, v59
	v_div_fmas_f32 v57, v57, v58, v60
	v_div_fixup_f32 v56, v57, v56, 1.0
	v_pk_mul_f32 v[28:29], v[28:29], v[56:57] op_sel_hi:[1,0]
	v_pk_mul_f32 v[30:31], v[30:31], v[56:57] op_sel_hi:[1,0]
	s_waitcnt vmcnt(0)
	s_nop 1
	v_mov_b32_e32 v46, v96
	v_mov_b32_e32 v47, v97
	v_mov_b32_e32 v48, v98
	v_mov_b32_e32 v49, v99
	v_pk_mul_f32 v[28:29], v[46:47], v[28:29]
	v_pk_mul_f32 v[30:31], v[48:49], v[30:31]
	v_cvt_pk_bf16_f32 v28, v28, v29
	v_cvt_pk_bf16_f32 v29, v30, v31
	global_store_dwordx2 v[50:51], v[28:29], off
	global_store_dwordx2 v[52:53], v[54:55], off
	s_nop 1
	v_mov_b32_e32 v28, v100
	v_mov_b32_e32 v29, v101
	v_mov_b32_e32 v30, v102
	v_mov_b32_e32 v31, v103
	v_cvt_pk_bf16_f32 v46, v24, v25
	v_cvt_pk_bf16_f32 v47, v26, v27
	v_pk_mul_f32 v[24:25], v[24:25], v[56:57] op_sel_hi:[1,0]
	v_pk_mul_f32 v[26:27], v[26:27], v[56:57] op_sel_hi:[1,0]
	v_pk_mul_f32 v[24:25], v[28:29], v[24:25]
	v_pk_mul_f32 v[26:27], v[30:31], v[26:27]
	v_cvt_pk_bf16_f32 v24, v24, v25
	v_cvt_pk_bf16_f32 v25, v26, v27
	global_store_dwordx2 v[50:51], v[24:25], off offset:512
	global_store_dwordx2 v[52:53], v[46:47], off offset:512
	s_nop 1
	v_mov_b32_e32 v24, v104
	v_mov_b32_e32 v25, v105
	v_mov_b32_e32 v26, v106
	v_mov_b32_e32 v27, v107
	v_cvt_pk_bf16_f32 v28, v20, v21
	v_cvt_pk_bf16_f32 v29, v22, v23
	v_pk_mul_f32 v[20:21], v[20:21], v[56:57] op_sel_hi:[1,0]
	v_pk_mul_f32 v[22:23], v[22:23], v[56:57] op_sel_hi:[1,0]
	v_pk_mul_f32 v[20:21], v[20:21], v[24:25]
	v_pk_mul_f32 v[22:23], v[22:23], v[26:27]
	v_cvt_pk_bf16_f32 v20, v20, v21
	v_cvt_pk_bf16_f32 v21, v22, v23
	global_store_dwordx2 v[50:51], v[20:21], off offset:1024
	global_store_dwordx2 v[52:53], v[28:29], off offset:1024
	s_nop 1
	v_mov_b32_e32 v20, v108
	v_mov_b32_e32 v21, v109
	v_mov_b32_e32 v22, v110
	v_mov_b32_e32 v23, v111
	v_cvt_pk_bf16_f32 v24, v16, v17
	v_cvt_pk_bf16_f32 v25, v18, v19
	v_pk_mul_f32 v[16:17], v[16:17], v[56:57] op_sel_hi:[1,0]
	v_pk_mul_f32 v[18:19], v[18:19], v[56:57] op_sel_hi:[1,0]
	v_pk_mul_f32 v[16:17], v[16:17], v[20:21]
	v_pk_mul_f32 v[18:19], v[18:19], v[22:23]
	v_cvt_pk_bf16_f32 v16, v16, v17
	v_cvt_pk_bf16_f32 v17, v18, v19
	global_store_dwordx2 v[50:51], v[16:17], off offset:1536
	global_store_dwordx2 v[52:53], v[24:25], off offset:1536
	s_nop 1
	v_mov_b32_e32 v16, v112
	v_mov_b32_e32 v17, v113
	v_mov_b32_e32 v18, v114
	v_mov_b32_e32 v19, v115
	v_cvt_pk_bf16_f32 v20, v8, v9
	v_cvt_pk_bf16_f32 v21, v10, v11
	v_pk_mul_f32 v[8:9], v[8:9], v[56:57] op_sel_hi:[1,0]
	v_pk_mul_f32 v[10:11], v[10:11], v[56:57] op_sel_hi:[1,0]
	v_pk_mul_f32 v[8:9], v[8:9], v[16:17]
	v_pk_mul_f32 v[10:11], v[10:11], v[18:19]
	v_cvt_pk_bf16_f32 v8, v8, v9
	v_cvt_pk_bf16_f32 v9, v10, v11
	global_store_dwordx2 v[50:51], v[8:9], off offset:2048
	global_store_dwordx2 v[52:53], v[20:21], off offset:2048
	s_nop 1
	v_mov_b32_e32 v8, v116
	v_mov_b32_e32 v9, v117
	v_mov_b32_e32 v10, v118
	v_mov_b32_e32 v11, v119
	v_cvt_pk_bf16_f32 v16, v12, v13
	v_cvt_pk_bf16_f32 v17, v14, v15
	v_pk_mul_f32 v[12:13], v[12:13], v[56:57] op_sel_hi:[1,0]
	v_pk_mul_f32 v[14:15], v[14:15], v[56:57] op_sel_hi:[1,0]
	v_pk_mul_f32 v[8:9], v[12:13], v[8:9]
	v_pk_mul_f32 v[10:11], v[14:15], v[10:11]
	v_cvt_pk_bf16_f32 v8, v8, v9
	v_cvt_pk_bf16_f32 v9, v10, v11
	global_store_dwordx2 v[50:51], v[8:9], off offset:2560
	global_store_dwordx2 v[52:53], v[16:17], off offset:2560
	s_nop 1
	v_mov_b32_e32 v8, v120
	v_mov_b32_e32 v9, v121
	v_mov_b32_e32 v10, v122
	v_mov_b32_e32 v11, v123
	v_cvt_pk_bf16_f32 v12, v4, v5
	v_cvt_pk_bf16_f32 v13, v6, v7
	v_pk_mul_f32 v[4:5], v[4:5], v[56:57] op_sel_hi:[1,0]
	v_pk_mul_f32 v[6:7], v[6:7], v[56:57] op_sel_hi:[1,0]
	v_pk_mul_f32 v[4:5], v[4:5], v[8:9]
	v_pk_mul_f32 v[6:7], v[6:7], v[10:11]
	v_cvt_pk_bf16_f32 v4, v4, v5
	v_cvt_pk_bf16_f32 v5, v6, v7
	global_store_dwordx2 v[50:51], v[4:5], off offset:3072
	global_store_dwordx2 v[52:53], v[12:13], off offset:3072
	s_nop 1
	v_mov_b32_e32 v4, v124
	v_mov_b32_e32 v5, v125
	v_mov_b32_e32 v6, v126
	v_mov_b32_e32 v7, v127
	v_cvt_pk_bf16_f32 v8, v0, v1
	v_cvt_pk_bf16_f32 v9, v2, v3
	v_pk_mul_f32 v[0:1], v[0:1], v[56:57] op_sel_hi:[1,0]
	v_pk_mul_f32 v[2:3], v[2:3], v[56:57] op_sel_hi:[1,0]
	v_pk_mul_f32 v[0:1], v[0:1], v[4:5]
	v_pk_mul_f32 v[2:3], v[2:3], v[6:7]
	v_cvt_pk_bf16_f32 v0, v0, v1
	v_cvt_pk_bf16_f32 v1, v2, v3
	global_store_dwordx2 v[50:51], v[0:1], off offset:3584
	global_store_dwordx2 v[52:53], v[8:9], off offset:3584
	s_cbranch_scc0 .LBB0_93

; __device__ __forceinline__ unsigned pk2(float lo, float hi) { return cvt_pk_bf16(lo, hi); }
; __device__ __forceinline__ void phase_norm(const Frame& F, const bf16* x, const float* gain, bf16* xn) {
;     for (int m = 2 * F.gw; m < T; m += 2 * F.NGW) {
;         v4u v[2][4]; float s[2] = {0.f, 0.f};
; #pragma unroll
;         for (int r = 0; r < 2; ++r) { const v4u* xr = (const v4u*)(x + (size_t)(m + r) * D) + F.lane;
; #pragma unroll
;             for (int j = 0; j < 4; ++j) v[r][j] = xr[64 * j]; }
; #pragma unroll
;         for (int r = 0; r < 2; ++r)
; #pragma unroll
;             for (int j = 0; j < 4; ++j)
; #pragma unroll
;                 for (int q = 0; q < 4; ++q) { const float a = bf_lo(v[r][j][q]), b = bf_hi(v[r][j][q]); s[r] += a * a + b * b; }
;         const f32x4* gr = (const f32x4*)gain + 2 * F.lane;
; #pragma unroll
;         for (int r = 0; r < 2; ++r) {
;             const float rstd = 1.0f / sqrtf(wave_sum(s[r]) * (1.0f / D) + 1e-6f);
;             v4u* o = (v4u*)(xn + (size_t)(m + r) * D) + F.lane;
; #pragma unroll
;             for (int j = 0; j < 4; ++j) { const f32x4 g0 = gr[128 * j], g1 = gr[128 * j + 1]; const v4u w = v[r][j]; v4u ow;
;                 ow.x = pk2(bf_lo(w.x) * rstd * g0.x, bf_hi(w.x) * rstd * g0.y); ow.y = pk2(bf_lo(w.y) * rstd * g0.z, bf_hi(w.y) * rstd * g0.w);
;                 ow.z = pk2(bf_lo(w.z) * rstd * g1.x, bf_hi(w.z) * rstd * g1.y); ow.w = pk2(bf_lo(w.w) * rstd * g1.z, bf_hi(w.w) * rstd * g1.w);
;                 o[64 * j] = ow; }
;         }
;     }
; }
.LBB0_144:
	v_readlane_b32 s6, v254, 42
	s_or_b32 s4, s4, s6
	s_cmp_eq_u32 s4, 0
	v_readlane_b32 s7, v254, 43
	s_cbranch_scc1 .LBB0_197
	v_readlane_b32 s4, v254, 17
	s_cmp_ge_i32 s4, s74
	s_cselect_b64 s[6:7], -1, 0
	s_cmp_lt_i32 s4, s75
	s_cselect_b64 s[4:5], -1, 0
	s_and_b64 s[4:5], s[6:7], s[4:5]
	s_andn2_b64 vcc, exec, s[4:5]
	s_cbranch_vccnz .LBB0_149
	s_mov_b32 s10, 0
	v_mbcnt_lo_u32_b32 v0, -1, 0
	v_mbcnt_hi_u32_b32 v0, -1, v0
	v_readlane_b32 s4, v254, 5
	v_readlane_b32 s12, v254, 1
	v_readlane_b32 s13, v254, 2
	v_add_u32_e32 v0, s4, v0
	s_load_dwordx2 s[4:5], s[12:13], 0xf8
	s_waitcnt lgkmcnt(0)
	v_readlane_b32 s14, v254, 0
	v_readfirstlane_b32 s8, v0
	s_ashr_i32 s9, s8, 6
	v_readlane_b32 s15, v254, 10
	s_mov_b32 s8, s15
	s_mov_b32 s11, s14
	s_lshl_b32 s11, s11, 3
	s_load_dwordx2 s[16:17], s[12:13], 0xf0
	s_waitcnt lgkmcnt(0)
	s_add_i32 s9, s11, s9
	s_cmpk_gt_i32 s9, 0x4fff
	s_cbranch_scc1 .LBB0_149
	s_lshl_b32 s8, s8, 4
	s_and_b64 s[12:13], s[44:45], exec
	s_cselect_b32 s11, 2, 25
	s_add_i32 s10, s10, s11
	s_ashr_i32 s11, s10, 31
	s_lshl_b64 s[10:11], s[10:11], 3
	v_readlane_b32 s12, v254, 1
	v_readlane_b32 s13, v254, 2
	s_add_u32 s10, s12, s10
	s_addc_u32 s11, s13, s11
	s_load_dwordx2 s[10:11], s[10:11], 0x0
	v_readlane_b32 s12, v254, 30
	v_readlane_b32 s13, v254, 31
	s_lshl_b64 s[12:13], s[12:13], 2
	v_and_b32_e32 v0, 63, v0
	s_waitcnt lgkmcnt(0)
	s_add_u32 s12, s10, s12
	v_lshlrev_b32_e32 v184, 5, v0
	s_addc_u32 s13, s11, s13
	s_lshl_b32 s10, s9, 1
	s_waitcnt vmcnt(0)
	v_lshl_add_u64 v[36:37], s[12:13], 0, v[184:185]
	s_mov_b64 s[12:13], 0x1000
	s_ashr_i32 s11, s10, 31
	v_lshl_add_u64 v[38:39], v[36:37], 0, s[12:13]
	s_mov_b64 s[12:13], 0x1800
	s_lshl_b64 s[18:19], s[10:11], 12
	v_lshl_add_u64 v[40:41], v[36:37], 0, s[12:13]
	s_add_u32 s12, s4, s18
	s_addc_u32 s13, s5, s19
	s_ashr_i32 s9, s8, 31
	s_lshl_b64 s[14:15], s[8:9], 12
	s_add_u32 s16, s16, s18
	v_lshlrev_b32_e32 v184, 4, v0
	s_addc_u32 s17, s17, s19
	global_load_dwordx4 v[132:135], v[36:37], off offset:16
	global_load_dwordx4 v[136:139], v[36:37], off
	global_load_dwordx4 v[140:143], v[36:37], off offset:2048
	global_load_dwordx4 v[144:147], v[36:37], off offset:2064
	global_load_dwordx4 v[148:151], v[38:39], off
	global_load_dwordx4 v[152:155], v[38:39], off offset:16
	global_load_dwordx4 v[156:159], v[40:41], off
	global_load_dwordx4 v[160:163], v[40:41], off offset:16
.LBB0_148:
	s_nop 0
	v_lshl_add_u64 v[2:3], s[12:13], 0, v[184:185]
	v_add_co_u32_e64 v44, s[4:5], s56, v2
	v_lshl_add_u64 v[0:1], s[16:17], 0, v[184:185]
	s_nop 0
	v_addc_co_u32_e64 v45, s[4:5], 0, v3, s[4:5]
	v_add_co_u32_e64 v42, s[4:5], s54, v2
	v_add_co_u32_e32 v4, vcc, 0xa000000, v0
	s_nop 0
	v_addc_co_u32_e64 v43, s[4:5], 0, v3, s[4:5]
	s_mov_b64 s[4:5], vcc
	s_nop 0
	v_addc_co_u32_e64 v5, s[4:5], 0, v1, s[4:5]
	v_add_co_u32_e32 v0, vcc, s87, v0
	global_load_dwordx4 v[16:19], v[4:5], off offset:3072
	global_load_dwordx4 v[48:51], v[4:5], off
	global_load_dwordx4 v[32:35], v[4:5], off offset:1024
	global_load_dwordx4 v[24:27], v[4:5], off offset:2048
	v_addc_co_u32_e32 v1, vcc, 0, v1, vcc
	global_load_dwordx4 v[12:15], v[0:1], off
	global_load_dwordx4 v[8:11], v[0:1], off offset:1024
	global_load_dwordx4 v[4:7], v[0:1], off offset:2048
	s_nop 0
	global_load_dwordx4 v[0:3], v[0:1], off offset:3072
	v_mbcnt_lo_u32_b32 v46, -1, 0
	v_mbcnt_hi_u32_b32 v46, -1, v46
	v_mbcnt_lo_u32_b32 v47, -1, 0
	v_mbcnt_hi_u32_b32 v47, -1, v47
	v_mbcnt_lo_u32_b32 v52, -1, 0
	v_mbcnt_hi_u32_b32 v52, -1, v52
	v_mbcnt_lo_u32_b32 v53, -1, 0
	v_mbcnt_hi_u32_b32 v53, -1, v53
	v_mbcnt_lo_u32_b32 v54, -1, 0
	v_mbcnt_hi_u32_b32 v54, -1, v54
	v_mbcnt_lo_u32_b32 v55, -1, 0
	v_mbcnt_hi_u32_b32 v55, -1, v55
	s_nop 0
	v_lshlrev_b32_e32 v46, 2, v46
	v_lshlrev_b32_e32 v47, 2, v47
	v_xor_b32_e32 v107, 4, v46
	v_xor_b32_e32 v108, 8, v47
	v_lshlrev_b32_e32 v52, 2, v52
	v_lshlrev_b32_e32 v53, 2, v53
	v_lshlrev_b32_e32 v54, 2, v54
	v_lshlrev_b32_e32 v55, 2, v55
	v_xor_b32_e32 v109, 16, v52
	v_xor_b32_e32 v110, 32, v53
	v_xor_b32_e32 v111, 64, v54
	v_xor_b32_e32 v112, 0x80, v55
	s_add_i32 s10, s10, s8
	s_add_u32 s12, s12, s14
	s_addc_u32 s13, s13, s15
	s_add_u32 s16, s16, s14
	s_addc_u32 s17, s17, s15
	s_cmp_lt_i32 s10, 0xa000
	s_waitcnt vmcnt(0)
	s_nop 1
	v_mov_b32_e32 v20, v132
	v_mov_b32_e32 v21, v133
	v_mov_b32_e32 v22, v134
	v_mov_b32_e32 v23, v135
	s_nop 1
	v_mov_b32_e32 v28, v136
	v_mov_b32_e32 v29, v137
	v_mov_b32_e32 v30, v138
	v_mov_b32_e32 v31, v139
	v_and_b32_e32 v47, 0xffff0000, v19
	v_and_b32_e32 v46, 0xffff0000, v18
	v_lshlrev_b32_e32 v72, 16, v49
	v_and_b32_e32 v73, 0xffff0000, v49
	v_lshlrev_b32_e32 v74, 16, v48
	v_and_b32_e32 v75, 0xffff0000, v48
	v_lshlrev_b32_e32 v67, 16, v19
	v_lshlrev_b32_e32 v66, 16, v18
	v_lshlrev_b32_e32 v68, 16, v51
	v_and_b32_e32 v69, 0xffff0000, v51
	v_lshlrev_b32_e32 v70, 16, v50
	v_and_b32_e32 v71, 0xffff0000, v50
	v_pk_mul_f32 v[76:77], v[46:47], v[46:47]
	v_pk_mul_f32 v[82:83], v[72:73], v[72:73]
	v_pk_mul_f32 v[84:85], v[74:75], v[74:75]
	v_lshlrev_b32_e32 v58, 16, v35
	v_and_b32_e32 v59, 0xffff0000, v35
	v_lshlrev_b32_e32 v60, 16, v34
	v_and_b32_e32 v61, 0xffff0000, v34
	v_lshlrev_b32_e32 v62, 16, v33
	v_and_b32_e32 v63, 0xffff0000, v33
	v_lshlrev_b32_e32 v64, 16, v32
	v_and_b32_e32 v65, 0xffff0000, v32
	v_lshlrev_b32_e32 v50, 16, v27
	v_and_b32_e32 v51, 0xffff0000, v27
	v_lshlrev_b32_e32 v52, 16, v26
	v_and_b32_e32 v53, 0xffff0000, v26
	v_lshlrev_b32_e32 v54, 16, v25
	v_and_b32_e32 v55, 0xffff0000, v25
	v_lshlrev_b32_e32 v56, 16, v24
	v_and_b32_e32 v57, 0xffff0000, v24
	v_lshlrev_b32_e32 v32, 16, v17
	v_and_b32_e32 v33, 0xffff0000, v17
	v_lshlrev_b32_e32 v34, 16, v16
; __device__ __forceinline__ unsigned pk2(float lo, float hi) { return cvt_pk_bf16(lo, hi); }
; __device__ __forceinline__ void phase_norm(const Frame& F, const bf16* x, const float* gain, bf16* xn) {
;     ...
;         for (int r = 0; r < 2; ++r)
; #pragma unroll
;             for (int j = 0; j < 4; ++j)
; #pragma unroll
;                 for (int q = 0; q < 4; ++q) { const float a = bf_lo(v[r][j][q]), b = bf_hi(v[r][j][q]); s[r] += a * a + b * b; }
;         const f32x4* gr = (const f32x4*)gain + 2 * F.lane;
; #pragma unroll
;         for (int r = 0; r < 2; ++r) {
;             const float rstd = 1.0f / sqrtf(wave_sum(s[r]) * (1.0f / D) + 1e-6f);
;             v4u* o = (v4u*)(xn + (size_t)(m + r) * D) + F.lane;
; #pragma unroll
;             for (int j = 0; j < 4; ++j) { const f32x4 g0 = gr[128 * j], g1 = gr[128 * j + 1]; const v4u w = v[r][j]; v4u ow;
;                 ow.x = pk2(bf_lo(w.x) * rstd * g0.x, bf_hi(w.x) * rstd * g0.y); ow.y = pk2(bf_lo(w.y) * rstd * g0.z, bf_hi(w.y) * rstd * g0.w);
;                 ow.z = pk2(bf_lo(w.z) * rstd * g1.x, bf_hi(w.z) * rstd * g1.y); ow.w = pk2(bf_lo(w.w) * rstd * g1.z, bf_hi(w.w) * rstd * g1.w);
;                 o[64 * j] = ow; }
	v_and_b32_e32 v35, 0xffff0000, v16
	v_pk_mul_f32 v[78:79], v[68:69], v[68:69]
	v_pk_mul_f32 v[80:81], v[70:71], v[70:71]
	v_lshlrev_b32_e32 v16, 16, v15
	v_and_b32_e32 v17, 0xffff0000, v15
	v_lshlrev_b32_e32 v18, 16, v14
	v_and_b32_e32 v19, 0xffff0000, v14
	v_lshlrev_b32_e32 v24, 16, v13
	v_and_b32_e32 v25, 0xffff0000, v13
	v_lshlrev_b32_e32 v26, 16, v12
	v_and_b32_e32 v27, 0xffff0000, v12
	v_lshlrev_b32_e32 v12, 16, v11
	v_and_b32_e32 v13, 0xffff0000, v11
	v_lshlrev_b32_e32 v14, 16, v10
	v_and_b32_e32 v15, 0xffff0000, v10
	v_lshlrev_b32_e32 v10, 16, v9
	v_and_b32_e32 v11, 0xffff0000, v9
	v_lshlrev_b32_e32 v48, 16, v8
	v_and_b32_e32 v49, 0xffff0000, v8
	v_pk_fma_f32 v[8:9], v[66:67], v[66:67], v[76:77]
	v_add_f32_e32 v76, v82, v83
	v_add_f32_e32 v77, v84, v85
	v_mov_b32_e32 v106, v66
	v_add_f32_e32 v66, v78, v79
	v_add_f32_e32 v78, v80, v81
	v_add_f32_e32 v76, v77, v76
	v_pk_mul_f32 v[92:93], v[64:65], v[64:65]
	v_add_f32_e32 v76, v78, v76
	v_pk_mul_f32 v[90:91], v[62:63], v[62:63]
	v_add_f32_e32 v79, v92, v93
	v_add_f32_e32 v66, v66, v76
	v_pk_mul_f32 v[88:89], v[60:61], v[60:61]
	v_add_f32_e32 v80, v90, v91
	v_add_f32_e32 v66, v79, v66
	v_pk_mul_f32 v[86:87], v[58:59], v[58:59]
	v_add_f32_e32 v81, v88, v89
	v_add_f32_e32 v66, v80, v66
	v_pk_mul_f32 v[98:99], v[56:57], v[56:57]
	v_add_f32_e32 v82, v86, v87
	v_add_f32_e32 v66, v81, v66
	v_pk_mul_f32 v[100:101], v[54:55], v[54:55]
	v_add_f32_e32 v83, v98, v99
	v_add_f32_e32 v66, v82, v66
	v_pk_mul_f32 v[96:97], v[52:53], v[52:53]
	v_add_f32_e32 v84, v100, v101
	v_add_f32_e32 v66, v83, v66
	v_pk_mul_f32 v[94:95], v[50:51], v[50:51]
	v_add_f32_e32 v85, v96, v97
	v_add_f32_e32 v66, v84, v66
	v_pk_mul_f32 v[102:103], v[34:35], v[34:35]
	v_add_f32_e32 v86, v94, v95
	v_add_f32_e32 v66, v85, v66
	v_pk_mul_f32 v[104:105], v[32:33], v[32:33]
	v_add_f32_e32 v87, v102, v103
	v_add_f32_e32 v66, v86, v66
	v_add_f32_e32 v88, v104, v105
	v_add_f32_e32 v66, v87, v66
	v_add_f32_e32 v66, v88, v66
	v_add_f32_e32 v8, v8, v66
	v_add_f32_e32 v8, v9, v8
	ds_bpermute_b32 v9, v107, v8
	v_mov_b32_e32 v107, v46
	v_mov_b32_e32 v46, v67
	v_pk_mul_f32 v[82:83], v[48:49], v[48:49]
	v_pk_mul_f32 v[80:81], v[10:11], v[10:11]
	s_waitcnt lgkmcnt(0)
	v_add_f32_e32 v8, v8, v9
	ds_bpermute_b32 v9, v108, v8
	s_waitcnt lgkmcnt(0)
	v_add_f32_e32 v8, v8, v9
	ds_bpermute_b32 v9, v109, v8
	s_waitcnt lgkmcnt(0)
	v_add_f32_e32 v8, v8, v9
	ds_bpermute_b32 v9, v110, v8
	s_waitcnt lgkmcnt(0)
	v_add_f32_e32 v8, v8, v9
	ds_bpermute_b32 v9, v111, v8
	s_waitcnt lgkmcnt(0)
	v_add_f32_e32 v8, v8, v9
	ds_bpermute_b32 v9, v112, v8
	s_waitcnt lgkmcnt(0)
	v_add_f32_e32 v8, v8, v9
	v_fmamk_f32 v8, v8, 0x3a000000, v208
	v_mul_f32_e32 v9, 0x4f800000, v8
	v_cmp_gt_f32_e32 vcc, s86, v8
	s_nop 1
	v_cndmask_b32_e32 v8, v8, v9, vcc
	v_sqrt_f32_e32 v9, v8
	s_nop 0
	v_add_u32_e32 v66, -1, v9
	v_add_u32_e32 v76, 1, v9
	v_fma_f32 v77, -v66, v9, v8
	v_fma_f32 v78, -v76, v9, v8
	v_cmp_ge_f32_e64 s[4:5], 0, v77
	s_nop 1
	v_cndmask_b32_e64 v9, v9, v66, s[4:5]
	v_cmp_lt_f32_e64 s[4:5], 0, v78
	s_nop 1
	v_cndmask_b32_e64 v9, v9, v76, s[4:5]
	v_mul_f32_e32 v66, 0x37800000, v9
	v_cndmask_b32_e32 v9, v9, v66, vcc
	v_cmp_class_f32_e32 vcc, v8, v204
	s_nop 1
	v_cndmask_b32_e32 v8, v9, v8, vcc
	v_div_scale_f32 v9, s[4:5], v8, v8, 1.0
	v_rcp_f32_e32 v76, v9
	v_div_scale_f32 v66, vcc, 1.0, v8, 1.0
	v_fma_f32 v77, -v9, v76, 1.0
	v_fmac_f32_e32 v76, v77, v76
	v_mul_f32_e32 v77, v66, v76
	v_fma_f32 v78, -v9, v77, v66
	v_fmac_f32_e32 v77, v78, v76
	v_fma_f32 v9, -v9, v77, v66
	v_div_fmas_f32 v9, v9, v76, v77
	v_div_fixup_f32 v66, v9, v8, 1.0
	v_pk_mul_f32 v[8:9], v[66:67], v[74:75] op_sel_hi:[0,1]
	v_pk_mul_f32 v[72:73], v[66:67], v[72:73] op_sel_hi:[0,1]
	v_pk_mul_f32 v[70:71], v[66:67], v[70:71] op_sel_hi:[0,1]
	v_pk_mul_f32 v[68:69], v[66:67], v[68:69] op_sel_hi:[0,1]
	v_pk_mul_f32 v[8:9], v[28:29], v[8:9]
	v_pk_mul_f32 v[28:29], v[30:31], v[72:73]
	v_pk_mul_f32 v[30:31], v[20:21], v[70:71]
	v_pk_mul_f32 v[68:69], v[22:23], v[68:69]
	v_cvt_pk_bf16_f32 v20, v8, v9
	v_cvt_pk_bf16_f32 v21, v28, v29
	v_cvt_pk_bf16_f32 v22, v30, v31
	v_cvt_pk_bf16_f32 v23, v68, v69
	global_store_dwordx4 v[42:43], v[20:23], off offset:-4096
	s_nop 1
	v_mov_b32_e32 v68, v140
	v_mov_b32_e32 v69, v141
	v_mov_b32_e32 v70, v142
	v_mov_b32_e32 v71, v143
	s_nop 1
	v_mov_b32_e32 v72, v144
	v_mov_b32_e32 v73, v145
	v_mov_b32_e32 v74, v146
	v_mov_b32_e32 v75, v147
	v_lshlrev_b32_e32 v20, 16, v7
	v_and_b32_e32 v21, 0xffff0000, v7
	v_lshlrev_b32_e32 v22, 16, v6
	v_and_b32_e32 v23, 0xffff0000, v6
	v_pk_mul_f32 v[6:7], v[66:67], v[64:65] op_sel_hi:[0,1]
	v_pk_mul_f32 v[62:63], v[66:67], v[62:63] op_sel_hi:[0,1]
	v_pk_mul_f32 v[60:61], v[66:67], v[60:61] op_sel_hi:[0,1]
	v_pk_mul_f32 v[58:59], v[66:67], v[58:59] op_sel_hi:[0,1]
	v_pk_mul_f32 v[78:79], v[14:15], v[14:15]
	v_lshlrev_b32_e32 v30, 16, v4
	v_and_b32_e32 v31, 0xffff0000, v4
	v_pk_mul_f32 v[76:77], v[12:13], v[12:13]
	v_lshlrev_b32_e32 v28, 16, v5
	v_and_b32_e32 v29, 0xffff0000, v5
	v_pk_mul_f32 v[90:91], v[30:31], v[30:31]
	v_pk_mul_f32 v[88:89], v[28:29], v[28:29]
	v_pk_mul_f32 v[86:87], v[22:23], v[22:23]
	v_pk_mul_f32 v[84:85], v[20:21], v[20:21]
	v_lshlrev_b32_e32 v4, 16, v1
	v_and_b32_e32 v5, 0xffff0000, v1
	v_lshlrev_b32_e32 v9, 16, v3
	v_lshlrev_b32_e32 v8, 16, v2
	v_and_b32_e32 v3, 0xffff0000, v3
	v_and_b32_e32 v2, 0xffff0000, v2
	v_pk_mul_f32 v[92:93], v[4:5], v[4:5]
	v_pk_mul_f32 v[6:7], v[68:69], v[6:7]
	v_pk_mul_f32 v[62:63], v[70:71], v[62:63]
	v_pk_mul_f32 v[60:61], v[72:73], v[60:61]
	v_pk_mul_f32 v[64:65], v[74:75], v[58:59]
	v_cvt_pk_bf16_f32 v58, v6, v7
	v_cvt_pk_bf16_f32 v59, v62, v63
	v_cvt_pk_bf16_f32 v60, v60, v61
; __device__ __forceinline__ unsigned pk2(float lo, float hi) { return cvt_pk_bf16(lo, hi); }
; __device__ __forceinline__ void phase_norm(const Frame& F, const bf16* x, const float* gain, bf16* xn) {
;     ...
;         for (int r = 0; r < 2; ++r) {
;             const float rstd = 1.0f / sqrtf(wave_sum(s[r]) * (1.0f / D) + 1e-6f);
;             v4u* o = (v4u*)(xn + (size_t)(m + r) * D) + F.lane;
; #pragma unroll
;             for (int j = 0; j < 4; ++j) { const f32x4 g0 = gr[128 * j], g1 = gr[128 * j + 1]; const v4u w = v[r][j]; v4u ow;
;                 ow.x = pk2(bf_lo(w.x) * rstd * g0.x, bf_hi(w.x) * rstd * g0.y); ow.y = pk2(bf_lo(w.y) * rstd * g0.z, bf_hi(w.y) * rstd * g0.w);
;                 ow.z = pk2(bf_lo(w.z) * rstd * g1.x, bf_hi(w.z) * rstd * g1.y); ow.w = pk2(bf_lo(w.w) * rstd * g1.z, bf_hi(w.w) * rstd * g1.w);
;                 o[64 * j] = ow; }
	v_cvt_pk_bf16_f32 v61, v64, v65
	global_store_dwordx4 v[44:45], v[58:61], off offset:1024
	s_nop 1
	v_mov_b32_e32 v58, v148
	v_mov_b32_e32 v59, v149
	v_mov_b32_e32 v60, v150
	v_mov_b32_e32 v61, v151
	s_nop 0
	s_nop 1
	v_mov_b32_e32 v62, v152
	v_mov_b32_e32 v63, v153
	v_mov_b32_e32 v64, v154
	v_mov_b32_e32 v65, v155
	v_pk_mul_f32 v[68:69], v[16:17], v[16:17]
	v_pk_mul_f32 v[72:73], v[24:25], v[24:25]
	v_add_f32_e32 v67, v68, v69
	v_pk_mul_f32 v[56:57], v[66:67], v[56:57] op_sel_hi:[0,1]
	v_pk_mul_f32 v[54:55], v[66:67], v[54:55] op_sel_hi:[0,1]
	v_pk_mul_f32 v[52:53], v[66:67], v[52:53] op_sel_hi:[0,1]
	v_pk_mul_f32 v[50:51], v[66:67], v[50:51] op_sel_hi:[0,1]
	v_pk_mul_f32 v[74:75], v[26:27], v[26:27]
	v_pk_mul_f32 v[70:71], v[18:19], v[18:19]
	v_add_f32_e32 v68, v72, v73
	v_lshlrev_b32_e32 v6, 16, v0
	v_and_b32_e32 v7, 0xffff0000, v0
	v_add_f32_e32 v69, v86, v87
	v_pk_mul_f32 v[94:95], v[6:7], v[6:7]
	v_pk_mul_f32 v[0:1], v[2:3], v[2:3]
	v_add_f32_e32 v72, v92, v93
	v_pk_fma_f32 v[0:1], v[8:9], v[8:9], v[0:1]
	v_pk_mul_f32 v[32:33], v[66:67], v[32:33] op_sel_hi:[0,1]
	v_pk_mul_f32 v[46:47], v[66:67], v[46:47] op_sel_hi:[0,1]
	v_pk_mul_f32 v[56:57], v[58:59], v[56:57]
	v_pk_mul_f32 v[54:55], v[60:61], v[54:55]
	v_pk_mul_f32 v[52:53], v[62:63], v[52:53]
	v_pk_mul_f32 v[58:59], v[64:65], v[50:51]
	v_cvt_pk_bf16_f32 v50, v56, v57
	v_cvt_pk_bf16_f32 v51, v54, v55
	v_cvt_pk_bf16_f32 v52, v52, v53
	v_cvt_pk_bf16_f32 v53, v58, v59
	global_store_dwordx4 v[44:45], v[50:53], off offset:2048
	s_nop 1
	v_mov_b32_e32 v50, v156
	v_mov_b32_e32 v51, v157
	v_mov_b32_e32 v52, v158
	v_mov_b32_e32 v53, v159
	s_nop 0
	s_nop 1
	v_mov_b32_e32 v54, v160
	v_mov_b32_e32 v55, v161
	v_mov_b32_e32 v56, v162
	v_mov_b32_e32 v57, v163
	v_add_f32_e32 v58, v74, v75
	v_add_f32_e32 v59, v70, v71
	v_add_f32_e32 v58, v58, v68
	v_add_f32_e32 v58, v59, v58
	v_add_f32_e32 v60, v82, v83
	v_add_f32_e32 v58, v67, v58
	v_add_f32_e32 v61, v80, v81
	v_add_f32_e32 v58, v60, v58
	v_add_f32_e32 v62, v78, v79
	v_add_f32_e32 v58, v61, v58
	v_add_f32_e32 v63, v76, v77
	v_add_f32_e32 v58, v62, v58
	v_add_f32_e32 v64, v90, v91
	v_add_f32_e32 v58, v63, v58
	v_add_f32_e32 v65, v88, v89
	v_add_f32_e32 v58, v64, v58
	v_add_f32_e32 v58, v65, v58
	v_add_f32_e32 v70, v84, v85
	v_add_f32_e32 v58, v69, v58
	v_add_f32_e32 v71, v94, v95
	v_add_f32_e32 v58, v70, v58
	v_add_f32_e32 v58, v71, v58
	v_add_f32_e32 v58, v72, v58
	v_add_f32_e32 v0, v0, v58
	v_add_f32_e32 v58, v1, v0
	v_pk_mul_f32 v[0:1], v[66:67], v[34:35] op_sel_hi:[0,1]
	v_pk_mul_f32 v[34:35], v[66:67], v[106:107] op_sel_hi:[0,1]
	v_pk_mul_f32 v[0:1], v[50:51], v[0:1]
	v_pk_mul_f32 v[50:51], v[52:53], v[32:33]
	v_pk_mul_f32 v[34:35], v[54:55], v[34:35]
	v_pk_mul_f32 v[46:47], v[56:57], v[46:47]
	v_cvt_pk_bf16_f32 v32, v0, v1
	v_cvt_pk_bf16_f32 v33, v50, v51
	v_cvt_pk_bf16_f32 v34, v34, v35
	v_cvt_pk_bf16_f32 v35, v46, v47
	global_store_dwordx4 v[44:45], v[32:35], off offset:3072
	v_mbcnt_lo_u32_b32 v0, -1, 0
	v_mbcnt_hi_u32_b32 v0, -1, v0
	v_mbcnt_lo_u32_b32 v1, -1, 0
	v_mbcnt_hi_u32_b32 v1, -1, v1
	v_mbcnt_lo_u32_b32 v50, -1, 0
	v_mbcnt_hi_u32_b32 v50, -1, v50
	v_mbcnt_lo_u32_b32 v51, -1, 0
	v_mbcnt_hi_u32_b32 v51, -1, v51
	v_mbcnt_lo_u32_b32 v52, -1, 0
	v_mbcnt_hi_u32_b32 v52, -1, v52
	v_mbcnt_lo_u32_b32 v53, -1, 0
	v_mbcnt_hi_u32_b32 v53, -1, v53
	s_nop 1
	v_mov_b32_e32 v32, v132
	v_mov_b32_e32 v33, v133
	v_mov_b32_e32 v34, v134
	v_mov_b32_e32 v35, v135
	s_nop 1
	v_mov_b32_e32 v44, v136
	v_mov_b32_e32 v45, v137
	v_mov_b32_e32 v46, v138
	v_mov_b32_e32 v47, v139
	v_lshlrev_b32_e32 v0, 2, v0
	v_xor_b32_e32 v0, 4, v0
	ds_bpermute_b32 v0, v0, v58
	v_lshlrev_b32_e32 v1, 2, v1
	v_xor_b32_e32 v1, 8, v1
	v_lshlrev_b32_e32 v50, 2, v50
	v_xor_b32_e32 v50, 16, v50
	s_waitcnt lgkmcnt(0)
	v_add_f32_e32 v0, v58, v0
	ds_bpermute_b32 v1, v1, v0
	v_lshlrev_b32_e32 v51, 2, v51
	v_xor_b32_e32 v51, 32, v51
	v_lshlrev_b32_e32 v52, 2, v52
	v_xor_b32_e32 v52, 64, v52
	s_waitcnt lgkmcnt(0)
	v_add_f32_e32 v0, v0, v1
	ds_bpermute_b32 v1, v50, v0
	v_lshlrev_b32_e32 v53, 2, v53
	v_xor_b32_e32 v53, 0x80, v53
	s_waitcnt lgkmcnt(0)
	v_add_f32_e32 v0, v0, v1
	ds_bpermute_b32 v1, v51, v0
	s_waitcnt lgkmcnt(0)
; __device__ __forceinline__ unsigned pk2(float lo, float hi) { return cvt_pk_bf16(lo, hi); }
; __device__ __forceinline__ void phase_norm(const Frame& F, const bf16* x, const float* gain, bf16* xn) {
;     ...
;         for (int r = 0; r < 2; ++r) {
;             const float rstd = 1.0f / sqrtf(wave_sum(s[r]) * (1.0f / D) + 1e-6f);
;             v4u* o = (v4u*)(xn + (size_t)(m + r) * D) + F.lane;
; #pragma unroll
;             for (int j = 0; j < 4; ++j) { const f32x4 g0 = gr[128 * j], g1 = gr[128 * j + 1]; const v4u w = v[r][j]; v4u ow;
;                 ow.x = pk2(bf_lo(w.x) * rstd * g0.x, bf_hi(w.x) * rstd * g0.y); ow.y = pk2(bf_lo(w.y) * rstd * g0.z, bf_hi(w.y) * rstd * g0.w);
;                 ow.z = pk2(bf_lo(w.z) * rstd * g1.x, bf_hi(w.z) * rstd * g1.y); ow.w = pk2(bf_lo(w.w) * rstd * g1.z, bf_hi(w.w) * rstd * g1.w);
;                 o[64 * j] = ow; }
	v_add_f32_e32 v0, v0, v1
	ds_bpermute_b32 v1, v52, v0
	s_waitcnt lgkmcnt(0)
	v_add_f32_e32 v0, v0, v1
	ds_bpermute_b32 v1, v53, v0
	s_waitcnt lgkmcnt(0)
	v_add_f32_e32 v0, v0, v1
	v_fmamk_f32 v0, v0, 0x3a000000, v208
	v_mul_f32_e32 v1, 0x4f800000, v0
	v_cmp_gt_f32_e32 vcc, s86, v0
	s_nop 1
	v_cndmask_b32_e32 v0, v0, v1, vcc
	v_sqrt_f32_e32 v1, v0
	s_nop 0
	v_add_u32_e32 v50, -1, v1
	v_add_u32_e32 v51, 1, v1
	v_fma_f32 v52, -v50, v1, v0
	v_fma_f32 v53, -v51, v1, v0
	v_cmp_ge_f32_e64 s[4:5], 0, v52
	s_nop 1
	v_cndmask_b32_e64 v1, v1, v50, s[4:5]
	v_cmp_lt_f32_e64 s[4:5], 0, v53
	s_nop 1
	v_cndmask_b32_e64 v1, v1, v51, s[4:5]
	v_mul_f32_e32 v50, 0x37800000, v1
	v_cndmask_b32_e32 v1, v1, v50, vcc
	v_cmp_class_f32_e32 vcc, v0, v204
	s_nop 1
	v_cndmask_b32_e32 v0, v1, v0, vcc
	v_div_scale_f32 v1, s[4:5], v0, v0, 1.0
	v_rcp_f32_e32 v51, v1
	v_div_scale_f32 v50, vcc, 1.0, v0, 1.0
	v_fma_f32 v52, -v1, v51, 1.0
	v_fmac_f32_e32 v51, v52, v51
	v_mul_f32_e32 v52, v50, v51
	v_fma_f32 v53, -v1, v52, v50
	v_fmac_f32_e32 v52, v53, v51
	v_fma_f32 v1, -v1, v52, v50
	v_div_fmas_f32 v1, v1, v51, v52
	v_div_fixup_f32 v0, v1, v0, 1.0
	v_pk_mul_f32 v[26:27], v[0:1], v[26:27] op_sel_hi:[0,1]
	v_pk_mul_f32 v[24:25], v[0:1], v[24:25] op_sel_hi:[0,1]
	v_pk_mul_f32 v[18:19], v[0:1], v[18:19] op_sel_hi:[0,1]
	v_pk_mul_f32 v[16:17], v[0:1], v[16:17] op_sel_hi:[0,1]
	v_pk_mul_f32 v[26:27], v[44:45], v[26:27]
	v_pk_mul_f32 v[24:25], v[46:47], v[24:25]
	v_pk_mul_f32 v[18:19], v[32:33], v[18:19]
	v_pk_mul_f32 v[32:33], v[34:35], v[16:17]
	v_cvt_pk_bf16_f32 v16, v26, v27
	v_cvt_pk_bf16_f32 v17, v24, v25
	v_cvt_pk_bf16_f32 v18, v18, v19
	v_cvt_pk_bf16_f32 v19, v32, v33
	global_store_dwordx4 v[42:43], v[16:19], off
	s_nop 1
	v_mov_b32_e32 v16, v140
	v_mov_b32_e32 v17, v141
	v_mov_b32_e32 v18, v142
	v_mov_b32_e32 v19, v143
	s_nop 0
	s_nop 1
	v_mov_b32_e32 v24, v144
	v_mov_b32_e32 v25, v145
	v_mov_b32_e32 v26, v146
	v_mov_b32_e32 v27, v147
	v_pk_mul_f32 v[32:33], v[0:1], v[48:49] op_sel_hi:[0,1]
	v_pk_mul_f32 v[10:11], v[0:1], v[10:11] op_sel_hi:[0,1]
	v_pk_mul_f32 v[14:15], v[0:1], v[14:15] op_sel_hi:[0,1]
	v_pk_mul_f32 v[12:13], v[0:1], v[12:13] op_sel_hi:[0,1]
	v_pk_mul_f32 v[22:23], v[0:1], v[22:23] op_sel_hi:[0,1]
	v_pk_mul_f32 v[20:21], v[0:1], v[20:21] op_sel_hi:[0,1]
	v_pk_mul_f32 v[6:7], v[0:1], v[6:7] op_sel_hi:[0,1]
	v_pk_mul_f32 v[4:5], v[0:1], v[4:5] op_sel_hi:[0,1]
	v_pk_mul_f32 v[16:17], v[16:17], v[32:33]
	v_pk_mul_f32 v[18:19], v[18:19], v[10:11]
	v_pk_mul_f32 v[14:15], v[24:25], v[14:15]
	v_pk_mul_f32 v[24:25], v[26:27], v[12:13]
	v_cvt_pk_bf16_f32 v10, v16, v17
	v_cvt_pk_bf16_f32 v11, v18, v19
	v_cvt_pk_bf16_f32 v12, v14, v15
	v_cvt_pk_bf16_f32 v13, v24, v25
	global_store_dwordx4 v[42:43], v[10:13], off offset:1024
	s_nop 1
	v_mov_b32_e32 v10, v148
	v_mov_b32_e32 v11, v149
	v_mov_b32_e32 v12, v150
	v_mov_b32_e32 v13, v151
	s_nop 0
	s_nop 1
	v_mov_b32_e32 v14, v152
	v_mov_b32_e32 v15, v153
	v_mov_b32_e32 v16, v154
	v_mov_b32_e32 v17, v155
	v_pk_mul_f32 v[18:19], v[0:1], v[30:31] op_sel_hi:[0,1]
	v_pk_mul_f32 v[24:25], v[0:1], v[28:29] op_sel_hi:[0,1]
	v_pk_mul_f32 v[10:11], v[18:19], v[10:11]
	v_pk_mul_f32 v[12:13], v[24:25], v[12:13]
	v_pk_mul_f32 v[14:15], v[22:23], v[14:15]
	v_pk_mul_f32 v[16:17], v[20:21], v[16:17]
	v_cvt_pk_bf16_f32 v10, v10, v11
	v_cvt_pk_bf16_f32 v11, v12, v13
	v_cvt_pk_bf16_f32 v12, v14, v15
	v_cvt_pk_bf16_f32 v13, v16, v17
	global_store_dwordx4 v[42:43], v[10:13], off offset:2048
	s_nop 1
	v_mov_b32_e32 v10, v156
	v_mov_b32_e32 v11, v157
	v_mov_b32_e32 v12, v158
	v_mov_b32_e32 v13, v159
	s_nop 0
	s_nop 1
	v_mov_b32_e32 v14, v160
	v_mov_b32_e32 v15, v161
	v_mov_b32_e32 v16, v162
	v_mov_b32_e32 v17, v163
	v_mov_b32_e32 v18, v8
	v_mov_b32_e32 v19, v2
	v_mov_b32_e32 v2, v9
	v_pk_mul_f32 v[8:9], v[0:1], v[18:19] op_sel_hi:[0,1]
	v_pk_mul_f32 v[0:1], v[0:1], v[2:3] op_sel_hi:[0,1]
	v_pk_mul_f32 v[2:3], v[6:7], v[10:11]
	v_pk_mul_f32 v[4:5], v[4:5], v[12:13]
	v_pk_mul_f32 v[6:7], v[8:9], v[14:15]
	v_pk_mul_f32 v[8:9], v[0:1], v[16:17]
	v_cvt_pk_bf16_f32 v0, v2, v3
	v_cvt_pk_bf16_f32 v1, v4, v5
	v_cvt_pk_bf16_f32 v2, v6, v7
	v_cvt_pk_bf16_f32 v3, v8, v9
	global_store_dwordx4 v[42:43], v[0:3], off offset:3072
	s_cbranch_scc1 .LBB0_148

; __device__ __forceinline__ unsigned pk2(float lo, float hi) { return cvt_pk_bf16(lo, hi); }
; __device__ __forceinline__ void phase_norm(const Frame& F, const bf16* x, const float* gain, bf16* xn) {
;     for (int m = 2 * F.gw; m < T; m += 2 * F.NGW) {
;         v4u v[2][4]; float s[2] = {0.f, 0.f};
; #pragma unroll
;         for (int r = 0; r < 2; ++r) { const v4u* xr = (const v4u*)(x + (size_t)(m + r) * D) + F.lane;
; #pragma unroll
;             for (int j = 0; j < 4; ++j) v[r][j] = xr[64 * j]; }
; #pragma unroll
;         for (int r = 0; r < 2; ++r)
; #pragma unroll
;             for (int j = 0; j < 4; ++j)
; #pragma unroll
;                 for (int q = 0; q < 4; ++q) { const float a = bf_lo(v[r][j][q]), b = bf_hi(v[r][j][q]); s[r] += a * a + b * b; }
;         const f32x4* gr = (const f32x4*)gain + 2 * F.lane;
; #pragma unroll
;         for (int r = 0; r < 2; ++r) {
;             const float rstd = 1.0f / sqrtf(wave_sum(s[r]) * (1.0f / D) + 1e-6f);
;             v4u* o = (v4u*)(xn + (size_t)(m + r) * D) + F.lane;
; #pragma unroll
;             for (int j = 0; j < 4; ++j) { const f32x4 g0 = gr[128 * j], g1 = gr[128 * j + 1]; const v4u w = v[r][j]; v4u ow;
;                 ow.x = pk2(bf_lo(w.x) * rstd * g0.x, bf_hi(w.x) * rstd * g0.y); ow.y = pk2(bf_lo(w.y) * rstd * g0.z, bf_hi(w.y) * rstd * g0.w);
;                 ow.z = pk2(bf_lo(w.z) * rstd * g1.x, bf_hi(w.z) * rstd * g1.y); ow.w = pk2(bf_lo(w.w) * rstd * g1.z, bf_hi(w.w) * rstd * g1.w);
;                 o[64 * j] = ow; }
;         }
;     }
; }
.LBB0_331:
	s_andn2_b64 vcc, exec, s[44:45]
	s_cbranch_vccnz .LBB0_142
	s_cmp_ge_i32 s52, s74
	s_cselect_b64 s[6:7], -1, 0
	s_and_b64 s[4:5], s[6:7], s[46:47]
	s_andn2_b64 vcc, exec, s[4:5]
	s_cbranch_vccnz .LBB0_336
	s_mov_b32 s10, 0
	v_mbcnt_lo_u32_b32 v0, -1, 0
	v_mbcnt_hi_u32_b32 v0, -1, v0
	v_readlane_b32 s4, v254, 5
	v_readlane_b32 s12, v254, 1
	v_readlane_b32 s13, v254, 2
	v_add_u32_e32 v0, s4, v0
	s_load_dwordx2 s[4:5], s[12:13], 0xf8
	s_waitcnt lgkmcnt(0)
	v_readlane_b32 s14, v254, 0
	v_readfirstlane_b32 s8, v0
	s_ashr_i32 s9, s8, 6
	v_readlane_b32 s15, v254, 10
	s_mov_b32 s8, s15
	s_mov_b32 s11, s14
	s_lshl_b32 s11, s11, 3
	s_load_dwordx2 s[16:17], s[12:13], 0xf0
	s_waitcnt lgkmcnt(0)
	s_add_i32 s9, s11, s9
	s_cmpk_gt_i32 s9, 0x4fff
	s_cbranch_scc1 .LBB0_336
	s_ashr_i32 s11, s10, 31
	s_lshl_b32 s8, s8, 4
	s_lshl_b64 s[10:11], s[10:11], 3
	v_readlane_b32 s12, v254, 1
	v_readlane_b32 s13, v254, 2
	s_add_u32 s10, s12, s10
	s_addc_u32 s11, s13, s11
	s_load_dwordx2 s[10:11], s[10:11], 0x30
	v_readlane_b32 s12, v254, 30
	v_readlane_b32 s13, v254, 31
	s_lshl_b64 s[12:13], s[12:13], 2
	v_and_b32_e32 v0, 63, v0
	s_waitcnt lgkmcnt(0)
	s_add_u32 s12, s10, s12
	s_addc_u32 s13, s11, s13
	s_lshl_b32 s10, s9, 1
	v_lshlrev_b32_e32 v184, 5, v0
	s_waitcnt vmcnt(0)
	v_lshl_add_u64 v[28:29], s[12:13], 0, v[184:185]
	s_mov_b64 s[12:13], 0x1000
	s_ashr_i32 s11, s10, 31
	v_lshl_add_u64 v[30:31], v[28:29], 0, s[12:13]
	s_mov_b64 s[12:13], 0x1800
	s_lshl_b64 s[18:19], s[10:11], 12
	v_lshl_add_u64 v[32:33], v[28:29], 0, s[12:13]
	s_add_u32 s12, s4, s18
	s_addc_u32 s13, s5, s19
	s_ashr_i32 s9, s8, 31
	s_lshl_b64 s[14:15], s[8:9], 12
	s_add_u32 s16, s16, s18
	v_lshlrev_b32_e32 v184, 4, v0
	s_addc_u32 s17, s17, s19
	global_load_dwordx4 v[132:135], v[28:29], off offset:16
	global_load_dwordx4 v[136:139], v[28:29], off
	global_load_dwordx4 v[140:143], v[28:29], off offset:2064
	global_load_dwordx4 v[144:147], v[28:29], off offset:2048
	global_load_dwordx4 v[148:151], v[30:31], off offset:16
	global_load_dwordx4 v[152:155], v[30:31], off
	global_load_dwordx4 v[156:159], v[32:33], off offset:16
	global_load_dwordx4 v[160:163], v[32:33], off
.LBB0_335:
	v_lshl_add_u64 v[0:1], s[16:17], 0, v[184:185]
	v_add_co_u32_e32 v2, vcc, 0xa000000, v0
	v_lshl_add_u64 v[44:45], s[12:13], 0, v[184:185]
	s_nop 0
	v_addc_co_u32_e32 v3, vcc, 0, v1, vcc
	global_load_dwordx4 v[46:49], v[2:3], off
	global_load_dwordx4 v[24:27], v[2:3], off offset:1024
	global_load_dwordx4 v[20:23], v[2:3], off offset:2048
	global_load_dwordx4 v[16:19], v[2:3], off offset:3072
	v_add_co_u32_e32 v0, vcc, s87, v0
	s_add_i32 s10, s10, s8
	s_nop 0
	v_addc_co_u32_e32 v1, vcc, 0, v1, vcc
	global_load_dwordx4 v[12:15], v[0:1], off
	global_load_dwordx4 v[8:11], v[0:1], off offset:1024
	global_load_dwordx4 v[4:7], v[0:1], off offset:2048
	s_nop 0
	global_load_dwordx4 v[0:3], v[0:1], off offset:3072
	v_mbcnt_lo_u32_b32 v42, -1, 0
	v_mbcnt_hi_u32_b32 v42, -1, v42
	s_add_u32 s12, s12, s14
	v_lshlrev_b32_e32 v42, 2, v42
	v_xor_b32_e32 v98, 4, v42
	v_mbcnt_lo_u32_b32 v42, -1, 0
	v_mbcnt_hi_u32_b32 v42, -1, v42
	s_addc_u32 s13, s13, s15
	v_lshlrev_b32_e32 v42, 2, v42
	v_xor_b32_e32 v99, 8, v42
	v_mbcnt_lo_u32_b32 v42, -1, 0
	v_mbcnt_hi_u32_b32 v42, -1, v42
	s_add_u32 s16, s16, s14
	v_lshlrev_b32_e32 v42, 2, v42
	v_xor_b32_e32 v100, 16, v42
	v_mbcnt_lo_u32_b32 v42, -1, 0
	v_mbcnt_hi_u32_b32 v42, -1, v42
	s_addc_u32 s17, s17, s15
	v_lshlrev_b32_e32 v42, 2, v42
	v_xor_b32_e32 v101, 32, v42
	v_mbcnt_lo_u32_b32 v42, -1, 0
	v_mbcnt_hi_u32_b32 v42, -1, v42
	s_cmp_lt_i32 s10, 0xa000
	v_lshlrev_b32_e32 v42, 2, v42
	v_xor_b32_e32 v102, 64, v42
	v_mbcnt_lo_u32_b32 v42, -1, 0
	v_mbcnt_hi_u32_b32 v42, -1, v42
	v_lshlrev_b32_e32 v42, 2, v42
	v_xor_b32_e32 v103, 0x80, v42
	s_waitcnt vmcnt(0)
	s_nop 1
	v_mov_b32_e32 v60, v132
	v_mov_b32_e32 v61, v133
	v_mov_b32_e32 v62, v134
	v_mov_b32_e32 v63, v135
	s_nop 1
	v_mov_b32_e32 v64, v136
	v_mov_b32_e32 v65, v137
	v_mov_b32_e32 v66, v138
	v_mov_b32_e32 v67, v139
	v_lshlrev_b32_e32 v68, 16, v49
	v_and_b32_e32 v69, 0xffff0000, v49
	v_lshlrev_b32_e32 v76, 16, v47
	v_and_b32_e32 v77, 0xffff0000, v47
	v_lshlrev_b32_e32 v80, 16, v46
	v_and_b32_e32 v81, 0xffff0000, v46
	v_pk_mul_f32 v[70:71], v[68:69], v[68:69]
	v_lshlrev_b32_e32 v72, 16, v48
	v_and_b32_e32 v73, 0xffff0000, v48
	v_pk_mul_f32 v[78:79], v[76:77], v[76:77]
	v_pk_mul_f32 v[82:83], v[80:81], v[80:81]
	v_pk_mul_f32 v[74:75], v[72:73], v[72:73]
	v_add_f32_e32 v70, v70, v71
	v_add_f32_e32 v71, v78, v79
	v_add_f32_e32 v78, v82, v83
	v_lshlrev_b32_e32 v58, 16, v24
	v_and_b32_e32 v59, 0xffff0000, v24
	v_add_f32_e32 v71, v78, v71
	v_add_f32_e32 v74, v74, v75
	v_lshlrev_b32_e32 v54, 16, v25
	v_and_b32_e32 v55, 0xffff0000, v25
	v_pk_mul_f32 v[24:25], v[58:59], v[58:59]
	v_add_f32_e32 v71, v74, v71
	v_lshlrev_b32_e32 v50, 16, v26
	v_and_b32_e32 v51, 0xffff0000, v26
	v_pk_mul_f32 v[86:87], v[54:55], v[54:55]
	v_add_f32_e32 v70, v70, v71
	v_add_f32_e32 v24, v24, v25
	v_lshlrev_b32_e32 v46, 16, v27
	v_and_b32_e32 v47, 0xffff0000, v27
	v_pk_mul_f32 v[26:27], v[50:51], v[50:51]
	v_add_f32_e32 v24, v24, v70
	v_add_f32_e32 v25, v86, v87
	v_pk_mul_f32 v[84:85], v[46:47], v[46:47]
	v_lshlrev_b32_e32 v56, 16, v20
	v_and_b32_e32 v57, 0xffff0000, v20
	v_add_f32_e32 v24, v25, v24
	v_add_f32_e32 v25, v26, v27
	v_lshlrev_b32_e32 v52, 16, v21
	v_and_b32_e32 v53, 0xffff0000, v21
	v_pk_mul_f32 v[94:95], v[56:57], v[56:57]
	v_add_f32_e32 v24, v25, v24
	v_add_f32_e32 v25, v84, v85
	v_lshlrev_b32_e32 v48, 16, v22
	v_and_b32_e32 v49, 0xffff0000, v22
	v_pk_mul_f32 v[92:93], v[52:53], v[52:53]
	v_add_f32_e32 v24, v25, v24
	v_add_f32_e32 v25, v94, v95
	v_lshlrev_b32_e32 v42, 16, v23
	v_and_b32_e32 v43, 0xffff0000, v23
	v_pk_mul_f32 v[90:91], v[48:49], v[48:49]
	v_add_f32_e32 v24, v25, v24
	v_add_f32_e32 v25, v92, v93
	v_pk_mul_f32 v[88:89], v[42:43], v[42:43]
	v_lshlrev_b32_e32 v20, 16, v16
	v_and_b32_e32 v21, 0xffff0000, v16
	v_add_f32_e32 v24, v25, v24
	v_add_f32_e32 v25, v90, v91
	v_lshlrev_b32_e32 v22, 16, v17
	v_and_b32_e32 v23, 0xffff0000, v17
	v_pk_mul_f32 v[16:17], v[20:21], v[20:21]
	v_add_f32_e32 v24, v25, v24
	v_add_f32_e32 v25, v88, v89
	v_and_b32_e32 v41, 0xffff0000, v19
	v_and_b32_e32 v40, 0xffff0000, v18
	v_pk_mul_f32 v[96:97], v[22:23], v[22:23]
	v_add_f32_e32 v24, v25, v24
	v_add_f32_e32 v16, v16, v17
	v_lshlrev_b32_e32 v39, 16, v19
	v_lshlrev_b32_e32 v38, 16, v18
	v_pk_mul_f32 v[18:19], v[40:41], v[40:41]
	v_add_f32_e32 v16, v16, v24
	v_add_f32_e32 v17, v96, v97
	v_pk_fma_f32 v[18:19], v[38:39], v[38:39], v[18:19]
	v_add_f32_e32 v16, v17, v16
	v_add_f32_e32 v16, v18, v16
	v_add_f32_e32 v16, v19, v16
	ds_bpermute_b32 v17, v98, v16
	v_lshlrev_b32_e32 v35, 16, v3
	v_lshlrev_b32_e32 v34, 16, v2
	v_and_b32_e32 v3, 0xffff0000, v3
	v_and_b32_e32 v2, 0xffff0000, v2
	s_waitcnt lgkmcnt(0)
; __device__ __forceinline__ unsigned pk2(float lo, float hi) { return cvt_pk_bf16(lo, hi); }
; __device__ __forceinline__ void phase_norm(const Frame& F, const bf16* x, const float* gain, bf16* xn) {
;     ...
;         for (int r = 0; r < 2; ++r) {
;             const float rstd = 1.0f / sqrtf(wave_sum(s[r]) * (1.0f / D) + 1e-6f);
;             v4u* o = (v4u*)(xn + (size_t)(m + r) * D) + F.lane;
; #pragma unroll
;             for (int j = 0; j < 4; ++j) { const f32x4 g0 = gr[128 * j], g1 = gr[128 * j + 1]; const v4u w = v[r][j]; v4u ow;
;                 ow.x = pk2(bf_lo(w.x) * rstd * g0.x, bf_hi(w.x) * rstd * g0.y); ow.y = pk2(bf_lo(w.y) * rstd * g0.z, bf_hi(w.y) * rstd * g0.w);
;                 ow.z = pk2(bf_lo(w.z) * rstd * g1.x, bf_hi(w.z) * rstd * g1.y); ow.w = pk2(bf_lo(w.w) * rstd * g1.z, bf_hi(w.w) * rstd * g1.w);
;                 o[64 * j] = ow; }
	v_add_f32_e32 v16, v16, v17
	ds_bpermute_b32 v17, v99, v16
	v_pk_mul_f32 v[36:37], v[2:3], v[2:3]
	s_waitcnt lgkmcnt(0)
	v_add_f32_e32 v16, v16, v17
	ds_bpermute_b32 v17, v100, v16
	v_pk_fma_f32 v[36:37], v[34:35], v[34:35], v[36:37]
	s_waitcnt lgkmcnt(0)
	v_add_f32_e32 v16, v16, v17
	ds_bpermute_b32 v17, v101, v16
	s_waitcnt lgkmcnt(0)
	v_add_f32_e32 v16, v16, v17
	ds_bpermute_b32 v17, v102, v16
	s_waitcnt lgkmcnt(0)
	v_add_f32_e32 v16, v16, v17
	ds_bpermute_b32 v17, v103, v16
	s_waitcnt lgkmcnt(0)
	v_add_f32_e32 v16, v16, v17
	v_fmamk_f32 v16, v16, 0x3a000000, v208
	v_cmp_gt_f32_e32 vcc, s86, v16
	v_mul_f32_e32 v17, 0x4f800000, v16
	s_nop 0
	v_cndmask_b32_e32 v16, v16, v17, vcc
	v_sqrt_f32_e32 v17, v16
	s_nop 0
	v_add_u32_e32 v18, -1, v17
	v_fma_f32 v19, -v18, v17, v16
	v_cmp_ge_f32_e64 s[4:5], 0, v19
	v_add_u32_e32 v19, 1, v17
	s_nop 0
	v_cndmask_b32_e64 v18, v17, v18, s[4:5]
	v_fma_f32 v17, -v19, v17, v16
	v_cmp_lt_f32_e64 s[4:5], 0, v17
	s_nop 1
	v_cndmask_b32_e64 v17, v18, v19, s[4:5]
	v_mul_f32_e32 v18, 0x37800000, v17
	v_cndmask_b32_e32 v17, v17, v18, vcc
	v_cmp_class_f32_e32 vcc, v16, v204
	s_nop 1
	v_cndmask_b32_e32 v16, v17, v16, vcc
	v_div_scale_f32 v17, s[4:5], v16, v16, 1.0
	v_rcp_f32_e32 v18, v17
	s_nop 0
	v_fma_f32 v19, -v17, v18, 1.0
	v_fmac_f32_e32 v18, v19, v18
	v_div_scale_f32 v19, vcc, 1.0, v16, 1.0
	v_mul_f32_e32 v24, v19, v18
	v_fma_f32 v25, -v17, v24, v19
	v_fmac_f32_e32 v24, v25, v18
	v_fma_f32 v17, -v17, v24, v19
	v_div_fmas_f32 v17, v17, v18, v24
	v_div_fixup_f32 v26, v17, v16, 1.0
	v_pk_mul_f32 v[16:17], v[26:27], v[80:81] op_sel_hi:[0,1]
	v_pk_mul_f32 v[18:19], v[26:27], v[76:77] op_sel_hi:[0,1]
	v_pk_mul_f32 v[16:17], v[64:65], v[16:17]
	v_pk_mul_f32 v[18:19], v[66:67], v[18:19]
	v_cvt_pk_bf16_f32 v16, v16, v17
	v_cvt_pk_bf16_f32 v17, v18, v19
	v_pk_mul_f32 v[18:19], v[26:27], v[72:73] op_sel_hi:[0,1]
	v_pk_mul_f32 v[18:19], v[60:61], v[18:19]
	v_pk_mul_f32 v[24:25], v[26:27], v[68:69] op_sel_hi:[0,1]
	v_add_co_u32_e32 v60, vcc, s56, v44
	v_pk_mul_f32 v[24:25], v[62:63], v[24:25]
	s_nop 0
	v_addc_co_u32_e32 v61, vcc, 0, v45, vcc
	v_cvt_pk_bf16_f32 v18, v18, v19
	v_cvt_pk_bf16_f32 v19, v24, v25
	v_add_co_u32_e32 v24, vcc, s54, v44
	v_pk_mul_f32 v[20:21], v[26:27], v[20:21] op_sel_hi:[0,1]
	s_nop 0
	v_addc_co_u32_e32 v25, vcc, 0, v45, vcc
	global_store_dwordx4 v[24:25], v[16:19], off offset:-4096
	s_nop 1
	v_mov_b32_e32 v16, v140
	v_mov_b32_e32 v17, v141
	v_mov_b32_e32 v18, v142
	v_mov_b32_e32 v19, v143
	s_nop 0
	s_nop 1
	v_mov_b32_e32 v62, v144
	v_mov_b32_e32 v63, v145
	v_mov_b32_e32 v64, v146
	v_mov_b32_e32 v65, v147
	v_pk_mul_f32 v[44:45], v[26:27], v[58:59] op_sel_hi:[0,1]
	v_pk_mul_f32 v[22:23], v[26:27], v[22:23] op_sel_hi:[0,1]
	v_pk_mul_f32 v[44:45], v[62:63], v[44:45]
	s_nop 0
	v_cvt_pk_bf16_f32 v62, v44, v45
	v_pk_mul_f32 v[44:45], v[26:27], v[54:55] op_sel_hi:[0,1]
	v_pk_mul_f32 v[44:45], v[64:65], v[44:45]
	s_nop 0
	v_cvt_pk_bf16_f32 v63, v44, v45
	v_pk_mul_f32 v[44:45], v[26:27], v[50:51] op_sel_hi:[0,1]
	v_pk_mul_f32 v[16:17], v[16:17], v[44:45]
	v_pk_mul_f32 v[50:51], v[26:27], v[56:57] op_sel_hi:[0,1]
	v_cvt_pk_bf16_f32 v64, v16, v17
	v_pk_mul_f32 v[16:17], v[26:27], v[46:47] op_sel_hi:[0,1]
	v_pk_mul_f32 v[16:17], v[18:19], v[16:17]
	s_nop 0
	v_cvt_pk_bf16_f32 v65, v16, v17
	global_store_dwordx4 v[60:61], v[62:65], off offset:1024
	s_nop 1
	v_mov_b32_e32 v16, v148
	v_mov_b32_e32 v17, v149
	v_mov_b32_e32 v18, v150
	v_mov_b32_e32 v19, v151
	s_nop 1
	v_mov_b32_e32 v44, v152
	v_mov_b32_e32 v45, v153
	v_mov_b32_e32 v46, v154
	v_mov_b32_e32 v47, v155
	v_pk_mul_f32 v[44:45], v[44:45], v[50:51]
	v_pk_mul_f32 v[50:51], v[26:27], v[52:53] op_sel_hi:[0,1]
	v_pk_mul_f32 v[46:47], v[46:47], v[50:51]
	v_cvt_pk_bf16_f32 v44, v44, v45
	v_cvt_pk_bf16_f32 v45, v46, v47
	v_pk_mul_f32 v[46:47], v[26:27], v[48:49] op_sel_hi:[0,1]
	v_pk_mul_f32 v[16:17], v[16:17], v[46:47]
	v_lshlrev_b32_e32 v50, 16, v8
	v_cvt_pk_bf16_f32 v46, v16, v17
	v_pk_mul_f32 v[16:17], v[26:27], v[42:43] op_sel_hi:[0,1]
	v_pk_mul_f32 v[16:17], v[18:19], v[16:17]
	v_and_b32_e32 v51, 0xffff0000, v8
	v_cvt_pk_bf16_f32 v47, v16, v17
	global_store_dwordx4 v[60:61], v[44:47], off offset:2048
	s_nop 1
	v_mov_b32_e32 v16, v156
	v_mov_b32_e32 v17, v157
	v_mov_b32_e32 v18, v158
	v_mov_b32_e32 v19, v159
	s_nop 0
	s_nop 1
	v_mov_b32_e32 v42, v160
	v_mov_b32_e32 v43, v161
	v_mov_b32_e32 v44, v162
	v_mov_b32_e32 v45, v163
	v_lshlrev_b32_e32 v48, 16, v9
	v_and_b32_e32 v49, 0xffff0000, v9
	v_pk_mul_f32 v[72:73], v[50:51], v[50:51]
	v_pk_mul_f32 v[68:69], v[48:49], v[48:49]
	v_lshlrev_b32_e32 v8, 16, v7
	v_and_b32_e32 v9, 0xffff0000, v7
	v_and_b32_e32 v7, 0xffff0000, v5
	v_pk_mul_f32 v[62:63], v[8:9], v[8:9]
	v_lshlrev_b32_e32 v46, 16, v0
	v_and_b32_e32 v47, 0xffff0000, v0
	v_pk_mul_f32 v[20:21], v[42:43], v[20:21]
	v_pk_mul_f32 v[22:23], v[44:45], v[22:23]
	v_cvt_pk_bf16_f32 v20, v20, v21
	v_cvt_pk_bf16_f32 v21, v22, v23
	v_mov_b32_e32 v22, v38
	v_mov_b32_e32 v23, v40
	v_pk_mul_f32 v[22:23], v[26:27], v[22:23] op_sel_hi:[0,1]
	v_pk_mul_f32 v[16:17], v[16:17], v[22:23]
	v_mov_b32_e32 v40, v39
	v_cvt_pk_bf16_f32 v22, v16, v17
	v_pk_mul_f32 v[16:17], v[26:27], v[40:41] op_sel_hi:[0,1]
	v_pk_mul_f32 v[16:17], v[18:19], v[16:17]
	v_lshlrev_b32_e32 v26, 16, v15
	v_cvt_pk_bf16_f32 v23, v16, v17
	global_store_dwordx4 v[60:61], v[20:23], off offset:3072
	v_mbcnt_lo_u32_b32 v16, -1, 0
	v_mbcnt_hi_u32_b32 v16, -1, v16
	v_and_b32_e32 v27, 0xffff0000, v15
	v_lshlrev_b32_e32 v16, 2, v16
	v_xor_b32_e32 v74, 4, v16
	v_mbcnt_lo_u32_b32 v16, -1, 0
	v_mbcnt_hi_u32_b32 v16, -1, v16
	v_lshlrev_b32_e32 v38, 16, v14
	v_lshlrev_b32_e32 v16, 2, v16
	v_xor_b32_e32 v75, 8, v16
; __device__ __forceinline__ unsigned pk2(float lo, float hi) { return cvt_pk_bf16(lo, hi); }
; __device__ __forceinline__ void phase_norm(const Frame& F, const bf16* x, const float* gain, bf16* xn) {
;     ...
;         for (int r = 0; r < 2; ++r)
; #pragma unroll
;             for (int j = 0; j < 4; ++j)
; #pragma unroll
;                 for (int q = 0; q < 4; ++q) { const float a = bf_lo(v[r][j][q]), b = bf_hi(v[r][j][q]); s[r] += a * a + b * b; }
;         const f32x4* gr = (const f32x4*)gain + 2 * F.lane;
; #pragma unroll
;         for (int r = 0; r < 2; ++r) {
;             const float rstd = 1.0f / sqrtf(wave_sum(s[r]) * (1.0f / D) + 1e-6f);
;             v4u* o = (v4u*)(xn + (size_t)(m + r) * D) + F.lane;
; #pragma unroll
;             for (int j = 0; j < 4; ++j) { const f32x4 g0 = gr[128 * j], g1 = gr[128 * j + 1]; const v4u w = v[r][j]; v4u ow;
;                 ow.x = pk2(bf_lo(w.x) * rstd * g0.x, bf_hi(w.x) * rstd * g0.y); ow.y = pk2(bf_lo(w.y) * rstd * g0.z, bf_hi(w.y) * rstd * g0.w);
;                 ow.z = pk2(bf_lo(w.z) * rstd * g1.x, bf_hi(w.z) * rstd * g1.y); ow.w = pk2(bf_lo(w.w) * rstd * g1.z, bf_hi(w.w) * rstd * g1.w);
;                 o[64 * j] = ow; }
	v_mbcnt_lo_u32_b32 v16, -1, 0
	v_mbcnt_hi_u32_b32 v16, -1, v16
	v_and_b32_e32 v39, 0xffff0000, v14
	v_lshlrev_b32_e32 v16, 2, v16
	v_xor_b32_e32 v76, 16, v16
	v_mbcnt_lo_u32_b32 v16, -1, 0
	v_mbcnt_hi_u32_b32 v16, -1, v16
	v_lshlrev_b32_e32 v14, 16, v13
	v_lshlrev_b32_e32 v16, 2, v16
	v_xor_b32_e32 v77, 32, v16
	v_mbcnt_lo_u32_b32 v16, -1, 0
	v_mbcnt_hi_u32_b32 v16, -1, v16
	v_and_b32_e32 v15, 0xffff0000, v13
	v_lshlrev_b32_e32 v40, 16, v12
	v_and_b32_e32 v41, 0xffff0000, v12
	v_lshlrev_b32_e32 v16, 2, v16
	v_pk_mul_f32 v[54:55], v[26:27], v[26:27]
	v_pk_mul_f32 v[56:57], v[14:15], v[14:15]
	v_pk_mul_f32 v[60:61], v[40:41], v[40:41]
	v_xor_b32_e32 v78, 64, v16
	v_mbcnt_lo_u32_b32 v16, -1, 0
	v_mbcnt_hi_u32_b32 v16, -1, v16
	v_pk_mul_f32 v[52:53], v[38:39], v[38:39]
	v_add_f32_e32 v54, v54, v55
	v_add_f32_e32 v55, v56, v57
	v_add_f32_e32 v56, v60, v61
	v_lshlrev_b32_e32 v16, 2, v16
	v_add_f32_e32 v55, v56, v55
	v_add_f32_e32 v52, v52, v53
	v_xor_b32_e32 v79, 0x80, v16
	s_nop 1
	v_mov_b32_e32 v16, v132
	v_mov_b32_e32 v17, v133
	v_mov_b32_e32 v18, v134
	v_mov_b32_e32 v19, v135
	s_nop 1
	v_mov_b32_e32 v20, v136
	v_mov_b32_e32 v21, v137
	v_mov_b32_e32 v22, v138
	v_mov_b32_e32 v23, v139
	v_add_f32_e32 v52, v52, v55
	v_lshlrev_b32_e32 v44, 16, v10
	v_and_b32_e32 v45, 0xffff0000, v10
	v_add_f32_e32 v52, v54, v52
	v_add_f32_e32 v53, v72, v73
	v_lshlrev_b32_e32 v12, 16, v11
	v_and_b32_e32 v13, 0xffff0000, v11
	v_pk_mul_f32 v[64:65], v[44:45], v[44:45]
	v_add_f32_e32 v52, v53, v52
	v_add_f32_e32 v53, v68, v69
	v_pk_mul_f32 v[58:59], v[12:13], v[12:13]
	v_lshlrev_b32_e32 v42, 16, v4
	v_and_b32_e32 v43, 0xffff0000, v4
	v_add_f32_e32 v52, v53, v52
	v_add_f32_e32 v53, v64, v65
	v_lshlrev_b32_e32 v10, 16, v6
	v_and_b32_e32 v11, 0xffff0000, v6
	v_lshlrev_b32_e32 v6, 16, v5
	v_pk_mul_f32 v[80:81], v[42:43], v[42:43]
	v_add_f32_e32 v52, v53, v52
	v_add_f32_e32 v53, v58, v59
	v_pk_mul_f32 v[70:71], v[6:7], v[6:7]
	v_add_f32_e32 v52, v53, v52
	v_add_f32_e32 v53, v80, v81
	v_pk_mul_f32 v[66:67], v[10:11], v[10:11]
	v_add_f32_e32 v52, v53, v52
	v_add_f32_e32 v53, v70, v71
	v_add_f32_e32 v52, v53, v52
	v_add_f32_e32 v53, v66, v67
	v_lshlrev_b32_e32 v4, 16, v1
	v_and_b32_e32 v5, 0xffff0000, v1
	v_pk_mul_f32 v[0:1], v[46:47], v[46:47]
	v_add_f32_e32 v52, v53, v52
	v_add_f32_e32 v53, v62, v63
	v_pk_mul_f32 v[82:83], v[4:5], v[4:5]
	v_add_f32_e32 v52, v53, v52
	v_add_f32_e32 v0, v0, v1
	v_add_f32_e32 v0, v0, v52
	v_add_f32_e32 v1, v82, v83
	v_add_f32_e32 v0, v1, v0
	v_add_f32_e32 v0, v36, v0
	v_add_f32_e32 v0, v37, v0
	ds_bpermute_b32 v1, v74, v0
	s_waitcnt lgkmcnt(0)
	v_add_f32_e32 v0, v0, v1
	ds_bpermute_b32 v1, v75, v0
	s_waitcnt lgkmcnt(0)
	v_add_f32_e32 v0, v0, v1
	ds_bpermute_b32 v1, v76, v0
	s_waitcnt lgkmcnt(0)
	v_add_f32_e32 v0, v0, v1
	ds_bpermute_b32 v1, v77, v0
	s_waitcnt lgkmcnt(0)
	v_add_f32_e32 v0, v0, v1
	ds_bpermute_b32 v1, v78, v0
	s_waitcnt lgkmcnt(0)
	v_add_f32_e32 v0, v0, v1
	ds_bpermute_b32 v1, v79, v0
	s_waitcnt lgkmcnt(0)
	v_add_f32_e32 v0, v0, v1
	v_fmamk_f32 v0, v0, 0x3a000000, v208
	v_cmp_gt_f32_e32 vcc, s86, v0
	v_mul_f32_e32 v1, 0x4f800000, v0
	s_nop 0
	v_cndmask_b32_e32 v0, v0, v1, vcc
	v_sqrt_f32_e32 v1, v0
	s_nop 0
	v_add_u32_e32 v36, -1, v1
	v_fma_f32 v37, -v36, v1, v0
	v_cmp_ge_f32_e64 s[4:5], 0, v37
	v_add_u32_e32 v37, 1, v1
	s_nop 0
	v_cndmask_b32_e64 v36, v1, v36, s[4:5]
	v_fma_f32 v1, -v37, v1, v0
	v_cmp_lt_f32_e64 s[4:5], 0, v1
	s_nop 1
	v_cndmask_b32_e64 v1, v36, v37, s[4:5]
	v_mul_f32_e32 v36, 0x37800000, v1
	v_cndmask_b32_e32 v1, v1, v36, vcc
	v_cmp_class_f32_e32 vcc, v0, v204
	s_nop 1
	v_cndmask_b32_e32 v0, v1, v0, vcc
	v_div_scale_f32 v1, s[4:5], v0, v0, 1.0
	v_rcp_f32_e32 v36, v1
	s_nop 0
	v_fma_f32 v37, -v1, v36, 1.0
	v_fmac_f32_e32 v36, v37, v36
	v_div_scale_f32 v37, vcc, 1.0, v0, 1.0
	v_mul_f32_e32 v52, v37, v36
	v_fma_f32 v53, -v1, v52, v37
	v_fmac_f32_e32 v52, v53, v36
	v_fma_f32 v1, -v1, v52, v37
	v_div_fmas_f32 v1, v1, v36, v52
	v_div_fixup_f32 v0, v1, v0, 1.0
	v_pk_mul_f32 v[36:37], v[0:1], v[40:41] op_sel_hi:[0,1]
	v_pk_mul_f32 v[14:15], v[0:1], v[14:15] op_sel_hi:[0,1]
	v_pk_mul_f32 v[20:21], v[20:21], v[36:37]
	v_pk_mul_f32 v[14:15], v[22:23], v[14:15]
	v_cvt_pk_bf16_f32 v20, v20, v21
	v_cvt_pk_bf16_f32 v21, v14, v15
	v_pk_mul_f32 v[14:15], v[0:1], v[38:39] op_sel_hi:[0,1]
	v_pk_mul_f32 v[14:15], v[16:17], v[14:15]
	v_pk_mul_f32 v[12:13], v[0:1], v[12:13] op_sel_hi:[0,1]
	v_cvt_pk_bf16_f32 v22, v14, v15
	v_pk_mul_f32 v[14:15], v[0:1], v[26:27] op_sel_hi:[0,1]
	v_pk_mul_f32 v[14:15], v[18:19], v[14:15]
	v_pk_mul_f32 v[6:7], v[0:1], v[6:7] op_sel_hi:[0,1]
	v_cvt_pk_bf16_f32 v23, v14, v15
	global_store_dwordx4 v[24:25], v[20:23], off
	s_nop 1
	v_mov_b32_e32 v14, v140
	v_mov_b32_e32 v15, v141
	v_mov_b32_e32 v16, v142
	v_mov_b32_e32 v17, v143
	s_nop 0
	s_nop 1
	v_mov_b32_e32 v18, v144
	v_mov_b32_e32 v19, v145
	v_mov_b32_e32 v20, v146
	v_mov_b32_e32 v21, v147
	v_pk_mul_f32 v[22:23], v[0:1], v[50:51] op_sel_hi:[0,1]
	v_pk_mul_f32 v[4:5], v[0:1], v[4:5] op_sel_hi:[0,1]
	v_pk_mul_f32 v[12:13], v[16:17], v[12:13]
	v_pk_mul_f32 v[18:19], v[18:19], v[22:23]
	v_pk_mul_f32 v[22:23], v[0:1], v[48:49] op_sel_hi:[0,1]
	v_pk_mul_f32 v[20:21], v[20:21], v[22:23]
	v_cvt_pk_bf16_f32 v18, v18, v19
	v_cvt_pk_bf16_f32 v19, v20, v21
	v_pk_mul_f32 v[20:21], v[0:1], v[44:45] op_sel_hi:[0,1]
	v_pk_mul_f32 v[14:15], v[14:15], v[20:21]
	v_cvt_pk_bf16_f32 v21, v12, v13
	v_cvt_pk_bf16_f32 v20, v14, v15
	global_store_dwordx4 v[24:25], v[18:21], off offset:1024
	s_nop 1
	v_mov_b32_e32 v12, v148
	v_mov_b32_e32 v13, v149
	v_mov_b32_e32 v14, v150
	v_mov_b32_e32 v15, v151
	s_nop 0
	s_nop 1
	v_mov_b32_e32 v16, v152
	v_mov_b32_e32 v17, v153
	v_mov_b32_e32 v18, v154
	v_mov_b32_e32 v19, v155
	v_pk_mul_f32 v[20:21], v[0:1], v[42:43] op_sel_hi:[0,1]
	v_pk_mul_f32 v[16:17], v[20:21], v[16:17]
	v_pk_mul_f32 v[6:7], v[6:7], v[18:19]
	v_cvt_pk_bf16_f32 v16, v16, v17
	v_cvt_pk_bf16_f32 v17, v6, v7
	v_pk_mul_f32 v[6:7], v[0:1], v[10:11] op_sel_hi:[0,1]
	v_pk_mul_f32 v[6:7], v[6:7], v[12:13]
	s_nop 0
	v_cvt_pk_bf16_f32 v18, v6, v7
	v_pk_mul_f32 v[6:7], v[0:1], v[8:9] op_sel_hi:[0,1]
	v_pk_mul_f32 v[6:7], v[6:7], v[14:15]
	v_pk_mul_f32 v[14:15], v[0:1], v[46:47] op_sel_hi:[0,1]
	v_cvt_pk_bf16_f32 v19, v6, v7
	global_store_dwordx4 v[24:25], v[16:19], off offset:2048
	s_nop 1
	v_mov_b32_e32 v6, v156
	v_mov_b32_e32 v7, v157
	v_mov_b32_e32 v8, v158
	v_mov_b32_e32 v9, v159
	s_nop 1
	v_mov_b32_e32 v10, v160
	v_mov_b32_e32 v11, v161
	v_mov_b32_e32 v12, v162
	v_mov_b32_e32 v13, v163
	v_pk_mul_f32 v[10:11], v[14:15], v[10:11]
	v_pk_mul_f32 v[4:5], v[4:5], v[12:13]
	v_cvt_pk_bf16_f32 v10, v10, v11
	v_cvt_pk_bf16_f32 v11, v4, v5
	v_mov_b32_e32 v4, v34
	v_mov_b32_e32 v5, v2
	v_mov_b32_e32 v2, v35
	v_pk_mul_f32 v[4:5], v[0:1], v[4:5] op_sel_hi:[0,1]
	v_pk_mul_f32 v[0:1], v[0:1], v[2:3] op_sel_hi:[0,1]
	v_pk_mul_f32 v[4:5], v[4:5], v[6:7]
	v_pk_mul_f32 v[0:1], v[0:1], v[8:9]
	v_cvt_pk_bf16_f32 v12, v4, v5
	v_cvt_pk_bf16_f32 v13, v0, v1
	global_store_dwordx4 v[24:25], v[10:13], off offset:3072
	s_cbranch_scc1 .LBB0_335

; __device__ __forceinline__ void phase_rwkv_pre(const Frame& F, const Args& a, int l) {
;     const bf16* CF = (const bf16*)(F.ws + WS_AR + AR_CF); unsigned short* RK = (unsigned short*)(F.ws + WS_AR + AR_RKVK); bf16* LR = (bf16*)(F.ws + WS_AR + AR_LR);
;     const float* cw = a.in[F.z + 10] + (size_t)l * 3 * 1920; const float* kk_w = a.in[F.z + 16] + (size_t)l * 512;
;     const int lane = F.lane;
;     for (int t = F.gw; t < T; t += F.NGW) {
;         const int s = t & 4095; const bool hp = s > 0, hn = s < 4095;
; #pragma unroll
;         for (int j = 0; j < 4; ++j) {
;             if (j == 3 && lane >= 48) continue;
;             const int cb = 512 * j + 8 * lane;
;             const v4u zc = {0u, 0u, 0u, 0u};
;             const v4u cur = *(const v4u*)(CF + (size_t)t * 2048 + cb);
;             const v4u prv = hp ? *(const v4u*)(CF + (size_t)(t - 1) * 2048 + cb) : zc;
;             const v4u nxt = hn ? *(const v4u*)(CF + (size_t)(t + 1) * 2048 + cb) : zc;
;             float o[8];
; #pragma unroll
;             for (int q = 0; q < 4; ++q) {
;                 const unsigned wc_ = cur[q], wp = prv[q], wn = nxt[q];
;                 const int c = cb + 2 * q;
;                 o[2 * q] = cw[c] * bf_lo(wp) + cw[1920 + c] * bf_lo(wc_) + cw[3840 + c] * bf_lo(wn);
;                 o[2 * q + 1] = cw[c + 1] * bf_hi(wp) + cw[1920 + c + 1] * bf_hi(wc_) + cw[3840 + c + 1] * bf_hi(wn);
;             }
;             if (j < 3) {
;                 v4u w; w.x = pkh2(o[0], o[1]); w.y = pkh2(o[2], o[3]); w.z = pkh2(o[4], o[5]); w.w = pkh2(o[6], o[7]);
;                 *(v4u*)(RK + (size_t)t * 2048 + cb) = w;
;                 if (j == 1) {
;                     float kv[8]; float ss = 0.f;
; #pragma unroll
;                     for (int e = 0; e < 8; ++e) { kv[e] = o[e] * kk_w[8 * lane + e]; ss += kv[e] * kv[e]; }
;                     ss += shfl_xor_(ss, 1); ss += shfl_xor_(ss, 2); ss += shfl_xor_(ss, 4);
;                     const float rn = 1.0f / sqrtf(ss + 1e-12f);
;                     v4u w2; w2.x = pkh2(kv[0] * rn, kv[1] * rn); w2.y = pkh2(kv[2] * rn, kv[3] * rn); w2.z = pkh2(kv[4] * rn, kv[5] * rn); w2.w = pkh2(kv[6] * rn, kv[7] * rn);
;                     *(v4u*)(RK + (size_t)t * 2048 + 1536 + 8 * lane) = w2;
.LBB0_451:
	s_cmp_ge_i32 s50, s74
	s_cselect_b64 s[16:17], -1, 0
	s_and_b64 s[4:5], s[16:17], s[44:45]
	s_andn2_b64 vcc, exec, s[4:5]
	s_cbranch_vccnz .LBB0_480
	s_mov_b32 s4, 0
	v_mbcnt_lo_u32_b32 v0, -1, 0
	v_mbcnt_hi_u32_b32 v0, -1, v0
	v_readlane_b32 s5, v254, 5
	v_readlane_b32 s8, v254, 1
	v_readlane_b32 s9, v254, 2
	v_add_u32_e32 v0, s5, v0
	s_load_dwordx2 s[10:11], s[8:9], 0xf8
	s_waitcnt lgkmcnt(0)
	v_readlane_b32 s7, v254, 0
	v_readfirstlane_b32 s5, v0
	v_readlane_b32 s13, v254, 10
	s_mov_b32 s12, s13
	s_mov_b32 s6, s7
	s_ashr_i32 s5, s5, 6
	s_lshl_b32 s6, s6, 3
	s_add_i32 s18, s6, s5
	s_load_dwordx2 s[6:7], s[8:9], 0xf0
	s_waitcnt lgkmcnt(0)
	s_cmp_gt_i32 s18, 0x9fff
	s_cbranch_scc1 .LBB0_480
	s_lshl_b32 s20, s12, 3
	s_add_u32 s34, s10, 0x21600000
	s_addc_u32 s35, s11, 0
	s_ashr_i32 s5, s4, 31
	s_lshl_b64 s[4:5], s[4:5], 3
	v_readlane_b32 s6, v254, 1
	v_readlane_b32 s7, v254, 2
	s_add_u32 s4, s6, s4
	s_addc_u32 s5, s7, s5
	s_load_dwordx2 s[6:7], s[4:5], 0x80
	s_load_dwordx2 s[8:9], s[4:5], 0x50
	v_readlane_b32 s14, v254, 32
	v_readlane_b32 s15, v254, 33
	v_and_b32_e32 v2, 63, v0
	s_waitcnt lgkmcnt(0)
	s_add_u32 s14, s6, s14
	s_addc_u32 s15, s7, s15
	v_readlane_b32 s6, v254, 42
	s_mulk_i32 s6, 0x5a00
	s_add_u32 s22, s8, s6
	v_lshlrev_b32_e32 v184, 5, v2
	s_addc_u32 s23, s9, 0
	s_waitcnt vmcnt(0)
	v_lshl_add_u64 v[28:29], s[14:15], 0, v[184:185]
	s_ashr_i32 s19, s18, 31
	s_mul_i32 s14, s18, 0x300
	s_mul_hi_i32 s13, s18, 0x300
	s_add_u32 s14, s10, s14
	v_lshl_add_u64 v[18:19], s[22:23], 0, v[184:185]
	v_or_b32_e32 v0, 0x1000, v184
	v_mov_b32_e32 v1, v185
	v_or_b32_e32 v184, 0x1800, v184
	s_addc_u32 s13, s11, s13
	s_mov_b64 s[24:25], 0x2600
	v_lshl_add_u64 v[30:31], s[22:23], 0, v[0:1]
	v_lshl_add_u64 v[36:37], s[22:23], 0, v[184:185]
	s_add_u32 s22, s14, 0x35600000
	v_lshl_add_u64 v[24:25], v[18:19], 0, s[24:25]
	s_mov_b64 s[24:25], 0x4400
	s_addc_u32 s23, s13, 0
	s_ashr_i32 s21, s20, 31
	s_mul_i32 s44, s12, 0x1800
	s_lshl_b64 s[12:13], s[18:19], 12
	v_readlane_b32 s7, v254, 43
	s_mov_b64 s[26:27], 0x1e00
	s_mov_b64 s[28:29], 0x3c00
	v_lshl_add_u64 v[26:27], v[18:19], 0, s[24:25]
	s_add_u32 s24, s10, s12
	v_cmp_gt_u32_e64 s[4:5], 48, v2
	v_lshlrev_b32_e32 v16, 3, v2
	v_cmp_lt_u32_e64 s[6:7], 15, v2
	v_cmp_lt_u32_e64 s[8:9], 31, v2
	v_lshl_add_u64 v[20:21], v[18:19], 0, s[26:27]
	v_lshl_add_u64 v[22:23], v[18:19], 0, s[28:29]
	v_lshl_add_u64 v[32:33], v[30:31], 0, s[26:27]
	v_lshl_add_u64 v[34:35], v[30:31], 0, s[28:29]
	v_lshl_add_u64 v[38:39], v[36:37], 0, s[26:27]
	v_lshl_add_u64 v[40:41], v[36:37], 0, s[28:29]
	v_lshlrev_b32_e32 v184, 4, v2
	s_addc_u32 s25, s11, s13
	s_lshl_b64 s[26:27], s[20:21], 12
	global_load_dwordx4 v[72:75], v[18:19], off offset:16
	global_load_dwordx4 v[76:79], v[18:19], off
	global_load_dwordx4 v[80:83], v[20:21], off offset:16
	global_load_dwordx4 v[84:87], v[20:21], off
	global_load_dwordx4 v[88:91], v[22:23], off offset:16
	global_load_dwordx4 v[92:95], v[22:23], off
	global_load_dwordx4 v[96:99], v[18:19], off offset:2064
	global_load_dwordx4 v[100:103], v[18:19], off offset:2048
	global_load_dwordx4 v[104:107], v[24:25], off offset:16
	global_load_dwordx4 v[108:111], v[24:25], off
	global_load_dwordx4 v[112:115], v[26:27], off offset:16
	global_load_dwordx4 v[116:119], v[26:27], off
	global_load_dwordx4 v[120:123], v[28:29], off offset:16
	global_load_dwordx4 v[124:127], v[28:29], off
	global_load_dwordx4 v[132:135], v[30:31], off offset:16
	global_load_dwordx4 v[136:139], v[30:31], off
	global_load_dwordx4 v[140:143], v[32:33], off offset:16
	global_load_dwordx4 v[144:147], v[32:33], off
	global_load_dwordx4 v[148:151], v[34:35], off offset:16
	global_load_dwordx4 v[152:155], v[34:35], off
	global_load_dwordx4 v[156:159], v[36:37], off offset:16
	global_load_dwordx4 v[160:163], v[36:37], off
	global_load_dwordx4 v[164:167], v[38:39], off offset:16
	global_load_dwordx4 v[168:171], v[38:39], off
	global_load_dwordx4 v[172:175], v[40:41], off offset:16
	global_load_dwordx4 v[176:179], v[40:41], off
	s_branch .LBB0_456

; __device__ __forceinline__ void phase_rwkv_pre(const Frame& F, const Args& a, int l) {
;     ...
;             const v4u cur = *(const v4u*)(CF + (size_t)t * 2048 + cb);
;             const v4u prv = hp ? *(const v4u*)(CF + (size_t)(t - 1) * 2048 + cb) : zc;
;             const v4u nxt = hn ? *(const v4u*)(CF + (size_t)(t + 1) * 2048 + cb) : zc;
;             float o[8];
; #pragma unroll
;             for (int q = 0; q < 4; ++q) {
;                 const unsigned wc_ = cur[q], wp = prv[q], wn = nxt[q];
;                 const int c = cb + 2 * q;
;                 o[2 * q] = cw[c] * bf_lo(wp) + cw[1920 + c] * bf_lo(wc_) + cw[3840 + c] * bf_lo(wn);
;                 o[2 * q + 1] = cw[c + 1] * bf_hi(wp) + cw[1920 + c + 1] * bf_hi(wc_) + cw[3840 + c + 1] * bf_hi(wn);
;             }
;             if (j < 3) {
;                 v4u w; w.x = pkh2(o[0], o[1]); w.y = pkh2(o[2], o[3]); w.z = pkh2(o[4], o[5]); w.w = pkh2(o[6], o[7]);
;                 *(v4u*)(RK + (size_t)t * 2048 + cb) = w;
.LBB0_461:
	s_waitcnt vmcnt(0)
	s_nop 1
	v_mov_b32_e32 v44, v72
	v_mov_b32_e32 v45, v73
	v_mov_b32_e32 v46, v74
	v_mov_b32_e32 v47, v75
	s_nop 1
	v_mov_b32_e32 v48, v76
	v_mov_b32_e32 v49, v77
	v_mov_b32_e32 v50, v78
	v_mov_b32_e32 v51, v79
	s_nop 1
	v_mov_b32_e32 v52, v80
	v_mov_b32_e32 v53, v81
	v_mov_b32_e32 v54, v82
	v_mov_b32_e32 v55, v83
	s_nop 1
	v_mov_b32_e32 v56, v84
	v_mov_b32_e32 v57, v85
	v_mov_b32_e32 v58, v86
	v_mov_b32_e32 v59, v87
	v_lshlrev_b32_e32 v60, 16, v4
	v_and_b32_e32 v61, 0xffff0000, v4
	v_lshlrev_b32_e32 v0, 16, v8
	v_and_b32_e32 v1, 0xffff0000, v8
	v_lshlrev_b32_e32 v8, 16, v5
	v_mov_b32_e32 v3, 0
	v_pk_mul_f32 v[56:57], v[56:57], v[60:61]
	v_pk_fma_f32 v[0:1], v[48:49], v[0:1], v[56:57]
	v_lshlrev_b32_e32 v48, 16, v12
	v_and_b32_e32 v49, 0xffff0000, v12
	s_nop 1
	v_mov_b32_e32 v60, v88
	v_mov_b32_e32 v61, v89
	v_mov_b32_e32 v62, v90
	v_mov_b32_e32 v63, v91
	s_nop 1
	v_mov_b32_e32 v64, v92
	v_mov_b32_e32 v65, v93
	v_mov_b32_e32 v66, v94
	v_mov_b32_e32 v67, v95
	v_pk_fma_f32 v[0:1], v[64:65], v[48:49], v[0:1]
	s_nop 0
	v_cvt_pk_f16_f32 v4, v0, v1
	v_lshlrev_b32_e32 v0, 16, v9
	v_and_b32_e32 v1, 0xffff0000, v9
	v_and_b32_e32 v9, 0xffff0000, v5
	v_pk_mul_f32 v[8:9], v[58:59], v[8:9]
	s_nop 0
	v_pk_fma_f32 v[0:1], v[50:51], v[0:1], v[8:9]
	v_lshlrev_b32_e32 v8, 16, v13
	v_and_b32_e32 v9, 0xffff0000, v13
	v_pk_fma_f32 v[0:1], v[66:67], v[8:9], v[0:1]
	v_lshlrev_b32_e32 v8, 16, v6
	v_and_b32_e32 v9, 0xffff0000, v6
	v_cvt_pk_f16_f32 v5, v0, v1
	v_lshlrev_b32_e32 v0, 16, v10
	v_and_b32_e32 v1, 0xffff0000, v10
	v_pk_mul_f32 v[8:9], v[52:53], v[8:9]
	s_nop 0
	v_pk_fma_f32 v[0:1], v[44:45], v[0:1], v[8:9]
	v_lshlrev_b32_e32 v8, 16, v14
	v_and_b32_e32 v9, 0xffff0000, v14
	v_pk_fma_f32 v[0:1], v[60:61], v[8:9], v[0:1]
	v_lshlrev_b32_e32 v8, 16, v7
	v_and_b32_e32 v9, 0xffff0000, v7
	v_cvt_pk_f16_f32 v6, v0, v1
	v_lshlrev_b32_e32 v0, 16, v11
	v_and_b32_e32 v1, 0xffff0000, v11
	v_pk_mul_f32 v[8:9], v[54:55], v[8:9]
	s_nop 0
	v_pk_fma_f32 v[0:1], v[46:47], v[0:1], v[8:9]
	v_lshlrev_b32_e32 v8, 16, v15
	v_and_b32_e32 v9, 0xffff0000, v15
	v_pk_fma_f32 v[0:1], v[62:63], v[8:9], v[0:1]
	s_nop 0
	v_cvt_pk_f16_f32 v7, v0, v1
	v_add_co_u32_e32 v0, vcc, 0x2b600000, v42
	s_nop 1
	v_addc_co_u32_e32 v1, vcc, 0, v43, vcc
	global_store_dwordx4 v[0:1], v[4:7], off
	v_add_co_u32_e32 v0, vcc, 0x21600000, v42
	s_nop 0
	v_mov_b32_e32 v4, 0
	v_addc_co_u32_e32 v1, vcc, 0, v43, vcc
	global_load_dwordx4 v[6:9], v[0:1], off offset:1024
	v_cndmask_b32_e64 v0, 0, 1, s[12:13]
	v_cmp_ne_u32_e64 s[10:11], 1, v0
	s_andn2_b64 vcc, exec, s[12:13]
	v_mov_b32_e32 v5, 0
	s_cbranch_vccnz .LBB0_463
	global_load_dwordx4 v[2:5], v17, s[28:29] offset:1024

; __device__ __forceinline__ float shfl_xor_(float v, int m) { return __builtin_bit_cast(float, __builtin_amdgcn_ds_bpermute((lane_id() ^ m) << 2, __builtin_bit_cast(int, v))); }
; __device__ __forceinline__ void phase_rwkv_pre(const Frame& F, const Args& a, int l) {
;     ...
;             const v4u cur = *(const v4u*)(CF + (size_t)t * 2048 + cb);
;             const v4u prv = hp ? *(const v4u*)(CF + (size_t)(t - 1) * 2048 + cb) : zc;
;             const v4u nxt = hn ? *(const v4u*)(CF + (size_t)(t + 1) * 2048 + cb) : zc;
;             float o[8];
; #pragma unroll
;             for (int q = 0; q < 4; ++q) {
;                 const unsigned wc_ = cur[q], wp = prv[q], wn = nxt[q];
;                 const int c = cb + 2 * q;
;                 o[2 * q] = cw[c] * bf_lo(wp) + cw[1920 + c] * bf_lo(wc_) + cw[3840 + c] * bf_lo(wn);
;                 o[2 * q + 1] = cw[c + 1] * bf_hi(wp) + cw[1920 + c + 1] * bf_hi(wc_) + cw[3840 + c + 1] * bf_hi(wn);
;             }
;             if (j < 3) {
;                 v4u w; w.x = pkh2(o[0], o[1]); w.y = pkh2(o[2], o[3]); w.z = pkh2(o[4], o[5]); w.w = pkh2(o[6], o[7]);
;                 *(v4u*)(RK + (size_t)t * 2048 + cb) = w;
;                 if (j == 1) {
;                     float kv[8]; float ss = 0.f;
; #pragma unroll
;                     for (int e = 0; e < 8; ++e) { kv[e] = o[e] * kk_w[8 * lane + e]; ss += kv[e] * kv[e]; }
;                     ss += shfl_xor_(ss, 1); ss += shfl_xor_(ss, 2); ss += shfl_xor_(ss, 4);
;                     const float rn = 1.0f / sqrtf(ss + 1e-12f);
;                     v4u w2; w2.x = pkh2(kv[0] * rn, kv[1] * rn); w2.y = pkh2(kv[2] * rn, kv[3] * rn); w2.z = pkh2(kv[4] * rn, kv[5] * rn); w2.w = pkh2(kv[6] * rn, kv[7] * rn);
;                     *(v4u*)(RK + (size_t)t * 2048 + 1536 + 8 * lane) = w2;
.LBB0_465:
	s_waitcnt vmcnt(0)
	s_nop 1
	v_mov_b32_e32 v44, v96
	v_mov_b32_e32 v45, v97
	v_mov_b32_e32 v46, v98
	v_mov_b32_e32 v47, v99
	s_nop 1
	v_mov_b32_e32 v48, v100
	v_mov_b32_e32 v49, v101
	v_mov_b32_e32 v50, v102
	v_mov_b32_e32 v51, v103
	s_nop 1
	v_mov_b32_e32 v52, v104
	v_mov_b32_e32 v53, v105
	v_mov_b32_e32 v54, v106
	v_mov_b32_e32 v55, v107
	s_nop 1
	v_mov_b32_e32 v56, v108
	v_mov_b32_e32 v57, v109
	v_mov_b32_e32 v58, v110
	v_mov_b32_e32 v59, v111
	v_lshlrev_b32_e32 v60, 16, v6
	v_and_b32_e32 v61, 0xffff0000, v6
	v_lshlrev_b32_e32 v14, 16, v2
	v_and_b32_e32 v15, 0xffff0000, v2
	v_lshlrev_b32_e32 v2, 16, v3
	v_and_b32_e32 v3, 0xffff0000, v3
	s_waitcnt vmcnt(0)
	v_pk_mul_f32 v[56:57], v[56:57], v[60:61]
	v_pk_fma_f32 v[14:15], v[48:49], v[14:15], v[56:57]
	v_lshlrev_b32_e32 v48, 16, v10
	v_and_b32_e32 v49, 0xffff0000, v10
	v_lshlrev_b32_e32 v10, 16, v11
	v_and_b32_e32 v11, 0xffff0000, v11
	s_nop 1
	v_mov_b32_e32 v60, v112
	v_mov_b32_e32 v61, v113
	v_mov_b32_e32 v62, v114
	v_mov_b32_e32 v63, v115
	s_nop 1
	v_mov_b32_e32 v64, v116
	v_mov_b32_e32 v65, v117
	v_mov_b32_e32 v66, v118
	v_mov_b32_e32 v67, v119
	v_pk_fma_f32 v[14:15], v[64:65], v[48:49], v[14:15]
	v_lshlrev_b32_e32 v48, 16, v7
	v_and_b32_e32 v49, 0xffff0000, v7
	v_pk_mul_f32 v[48:49], v[58:59], v[48:49]
	v_cvt_pk_f16_f32 v6, v14, v15
	v_pk_fma_f32 v[2:3], v[50:51], v[2:3], v[48:49]
	s_nop 0
	v_pk_fma_f32 v[48:49], v[66:67], v[10:11], v[2:3]
	v_lshlrev_b32_e32 v10, 16, v8
	v_and_b32_e32 v11, 0xffff0000, v8
	v_lshlrev_b32_e32 v2, 16, v4
	v_and_b32_e32 v3, 0xffff0000, v4
	v_pk_mul_f32 v[10:11], v[52:53], v[10:11]
	v_lshlrev_b32_e32 v4, 16, v9
	v_pk_fma_f32 v[2:3], v[44:45], v[2:3], v[10:11]
	v_lshlrev_b32_e32 v10, 16, v12
	v_and_b32_e32 v11, 0xffff0000, v12
	v_pk_fma_f32 v[44:45], v[60:61], v[10:11], v[2:3]
	v_lshlrev_b32_e32 v2, 16, v5
	v_and_b32_e32 v3, 0xffff0000, v5
	v_and_b32_e32 v5, 0xffff0000, v9
	v_pk_mul_f32 v[4:5], v[54:55], v[4:5]
	v_cvt_pk_f16_f32 v7, v48, v49
	v_pk_fma_f32 v[2:3], v[46:47], v[2:3], v[4:5]
	v_lshlrev_b32_e32 v4, 16, v13
	v_and_b32_e32 v5, 0xffff0000, v13
	v_pk_fma_f32 v[4:5], v[62:63], v[4:5], v[2:3]
	v_add_co_u32_e32 v2, vcc, s68, v42
	v_cvt_pk_f16_f32 v8, v44, v45
	v_cvt_pk_f16_f32 v9, v4, v5
	v_addc_co_u32_e32 v3, vcc, 0, v43, vcc
	global_store_dwordx4 v[2:3], v[6:9], off offset:1024
	s_nop 0
	s_nop 1
	v_mov_b32_e32 v6, v120
	v_mov_b32_e32 v7, v121
	v_mov_b32_e32 v8, v122
	v_mov_b32_e32 v9, v123
	s_nop 1
	v_mov_b32_e32 v10, v124
	v_mov_b32_e32 v11, v125
	v_mov_b32_e32 v12, v126
	v_mov_b32_e32 v13, v127
	v_pk_mul_f32 v[4:5], v[4:5], v[8:9]
	v_pk_mul_f32 v[10:11], v[14:15], v[10:11]
	v_pk_mul_f32 v[8:9], v[48:49], v[12:13]
	v_pk_mul_f32 v[14:15], v[10:11], v[10:11]
	v_pk_mul_f32 v[12:13], v[8:9], v[8:9]
	v_add_f32_e32 v1, v14, v15
	v_pk_mul_f32 v[6:7], v[44:45], v[6:7]
	v_add_f32_e32 v1, v1, v12
	v_pk_mul_f32 v[44:45], v[6:7], v[6:7]
	v_add_f32_e32 v1, v1, v13
	v_add_f32_e32 v1, v1, v44
	v_pk_mul_f32 v[46:47], v[4:5], v[4:5]
	v_add_f32_e32 v1, v1, v45
	v_mbcnt_lo_u32_b32 v12, -1, 0
	v_mbcnt_hi_u32_b32 v12, -1, v12
	v_add_f32_e32 v1, v1, v46
	v_lshlrev_b32_e32 v12, 2, v12
	v_add_f32_e32 v1, v1, v47
	v_xor_b32_e32 v12, 4, v12
	ds_bpermute_b32 v12, v12, v1
	s_waitcnt lgkmcnt(0)
	v_add_f32_e32 v1, v1, v12
	v_mbcnt_lo_u32_b32 v12, -1, 0
	v_mbcnt_hi_u32_b32 v12, -1, v12
	s_nop 0
	v_lshlrev_b32_e32 v12, 2, v12
	v_xor_b32_e32 v12, 8, v12
	ds_bpermute_b32 v12, v12, v1
	s_waitcnt lgkmcnt(0)
	v_add_f32_e32 v1, v1, v12
	v_mbcnt_lo_u32_b32 v12, -1, 0
	v_mbcnt_hi_u32_b32 v12, -1, v12
	s_nop 0
	v_lshlrev_b32_e32 v12, 2, v12
	v_xor_b32_e32 v12, 16, v12
	ds_bpermute_b32 v12, v12, v1
	s_waitcnt lgkmcnt(0)
	v_add_f32_e32 v1, v1, v12
	v_add_f32_e32 v1, 0x2b8cbccc, v1
	v_cmp_gt_f32_e32 vcc, s86, v1
	v_mul_f32_e32 v12, 0x4f800000, v1
	s_nop 0
	v_cndmask_b32_e32 v1, v1, v12, vcc
	v_sqrt_f32_e32 v12, v1
	s_nop 0
	v_add_u32_e32 v13, -1, v12
	v_fma_f32 v14, -v13, v12, v1
	v_cmp_ge_f32_e64 s[14:15], 0, v14
	v_add_u32_e32 v14, 1, v12
	s_nop 0
	v_cndmask_b32_e64 v13, v12, v13, s[14:15]
	v_fma_f32 v12, -v14, v12, v1
	v_cmp_lt_f32_e64 s[14:15], 0, v12
	s_nop 1
	v_cndmask_b32_e64 v12, v13, v14, s[14:15]
	v_mul_f32_e32 v13, 0x37800000, v12
	v_cndmask_b32_e32 v12, v12, v13, vcc
	v_cmp_class_f32_e32 vcc, v1, v204
	s_nop 1
	v_cndmask_b32_e32 v1, v12, v1, vcc
	v_div_scale_f32 v12, s[14:15], v1, v1, 1.0
	v_rcp_f32_e32 v13, v12
	s_nop 0
	v_fma_f32 v14, -v12, v13, 1.0
	v_fmac_f32_e32 v13, v14, v13
	v_div_scale_f32 v14, vcc, 1.0, v1, 1.0
	v_mul_f32_e32 v15, v14, v13
	v_fma_f32 v44, -v12, v15, v14
	v_fmac_f32_e32 v15, v44, v13
	v_fma_f32 v12, -v12, v15, v14
	v_div_fmas_f32 v12, v12, v13, v15
	v_div_fixup_f32 v14, v12, v1, 1.0
	v_pk_mul_f32 v[10:11], v[10:11], v[14:15] op_sel_hi:[1,0]
	v_pk_mul_f32 v[8:9], v[8:9], v[14:15] op_sel_hi:[1,0]
	v_pk_mul_f32 v[6:7], v[6:7], v[14:15] op_sel_hi:[1,0]
	v_pk_mul_f32 v[4:5], v[4:5], v[14:15] op_sel_hi:[1,0]
	v_cvt_pk_f16_f32 v10, v10, v11
	v_cvt_pk_f16_f32 v11, v8, v9
	v_cvt_pk_f16_f32 v12, v6, v7
	v_cvt_pk_f16_f32 v13, v4, v5
	global_store_dwordx4 v[2:3], v[10:13], off offset:3072
	v_add_co_u32_e32 v2, vcc, 0x21600000, v42
	v_mov_b32_e32 v1, 0
	s_nop 0
	v_addc_co_u32_e32 v3, vcc, 0, v43, vcc
	global_load_dwordx4 v[4:7], v[2:3], off offset:2048
	s_and_b64 vcc, exec, s[10:11]
	v_mov_b32_e32 v2, 0
	v_mov_b32_e32 v3, 0
	s_cbranch_vccnz .LBB0_467
	global_load_dwordx4 v[0:3], v17, s[28:29] offset:2048

; __device__ __forceinline__ void phase_rwkv_pre(const Frame& F, const Args& a, int l) {
;     ...
;             const v4u cur = *(const v4u*)(CF + (size_t)t * 2048 + cb);
;             const v4u prv = hp ? *(const v4u*)(CF + (size_t)(t - 1) * 2048 + cb) : zc;
;             const v4u nxt = hn ? *(const v4u*)(CF + (size_t)(t + 1) * 2048 + cb) : zc;
;             float o[8];
; #pragma unroll
;             for (int q = 0; q < 4; ++q) {
;                 const unsigned wc_ = cur[q], wp = prv[q], wn = nxt[q];
;                 const int c = cb + 2 * q;
;                 o[2 * q] = cw[c] * bf_lo(wp) + cw[1920 + c] * bf_lo(wc_) + cw[3840 + c] * bf_lo(wn);
;                 o[2 * q + 1] = cw[c + 1] * bf_hi(wp) + cw[1920 + c + 1] * bf_hi(wc_) + cw[3840 + c + 1] * bf_hi(wn);
;             }
;             if (j < 3) {
;                 v4u w; w.x = pkh2(o[0], o[1]); w.y = pkh2(o[2], o[3]); w.z = pkh2(o[4], o[5]); w.w = pkh2(o[6], o[7]);
;                 *(v4u*)(RK + (size_t)t * 2048 + cb) = w;
.LBB0_469:
	s_waitcnt vmcnt(0)
	s_nop 1
	v_mov_b32_e32 v12, v132
	v_mov_b32_e32 v13, v133
	v_mov_b32_e32 v14, v134
	v_mov_b32_e32 v15, v135
	s_nop 1
	v_mov_b32_e32 v44, v136
	v_mov_b32_e32 v45, v137
	v_mov_b32_e32 v46, v138
	v_mov_b32_e32 v47, v139
	s_nop 1
	v_mov_b32_e32 v48, v140
	v_mov_b32_e32 v49, v141
	v_mov_b32_e32 v50, v142
	v_mov_b32_e32 v51, v143
	s_nop 1
	v_mov_b32_e32 v52, v144
	v_mov_b32_e32 v53, v145
	v_mov_b32_e32 v54, v146
	v_mov_b32_e32 v55, v147
	v_lshlrev_b32_e32 v58, 16, v4
	v_and_b32_e32 v59, 0xffff0000, v4
	v_lshlrev_b32_e32 v56, 16, v0
	v_and_b32_e32 v57, 0xffff0000, v0
	v_lshlrev_b32_e32 v4, 16, v5
	v_and_b32_e32 v5, 0xffff0000, v5
	s_waitcnt vmcnt(0)
	v_pk_mul_f32 v[52:53], v[52:53], v[58:59]
	s_nop 0
	v_pk_fma_f32 v[44:45], v[44:45], v[56:57], v[52:53]
	v_lshlrev_b32_e32 v52, 16, v8
	v_and_b32_e32 v53, 0xffff0000, v8
	v_pk_mul_f32 v[4:5], v[54:55], v[4:5]
	v_lshlrev_b32_e32 v8, 16, v9
	v_and_b32_e32 v9, 0xffff0000, v9
	s_nop 1
	v_mov_b32_e32 v56, v148
	v_mov_b32_e32 v57, v149
	v_mov_b32_e32 v58, v150
	v_mov_b32_e32 v59, v151
	s_nop 1
	v_mov_b32_e32 v60, v152
	v_mov_b32_e32 v61, v153
	v_mov_b32_e32 v62, v154
	v_mov_b32_e32 v63, v155
	v_pk_fma_f32 v[44:45], v[60:61], v[52:53], v[44:45]
	s_nop 0
	v_cvt_pk_f16_f32 v0, v44, v45
	v_lshlrev_b32_e32 v44, 16, v1
	v_and_b32_e32 v45, 0xffff0000, v1
	v_pk_fma_f32 v[4:5], v[46:47], v[44:45], v[4:5]
	s_nop 0
	v_pk_fma_f32 v[4:5], v[62:63], v[8:9], v[4:5]
	v_lshlrev_b32_e32 v8, 16, v6
	v_and_b32_e32 v9, 0xffff0000, v6
	v_cvt_pk_f16_f32 v1, v4, v5
	v_lshlrev_b32_e32 v4, 16, v2
	v_and_b32_e32 v5, 0xffff0000, v2
	v_pk_mul_f32 v[8:9], v[48:49], v[8:9]
	v_lshlrev_b32_e32 v6, 16, v7
	v_pk_fma_f32 v[4:5], v[12:13], v[4:5], v[8:9]
	v_lshlrev_b32_e32 v8, 16, v10
	v_and_b32_e32 v9, 0xffff0000, v10
	v_pk_fma_f32 v[4:5], v[56:57], v[8:9], v[4:5]
	v_and_b32_e32 v7, 0xffff0000, v7
	v_cvt_pk_f16_f32 v2, v4, v5
	v_lshlrev_b32_e32 v4, 16, v3
	v_and_b32_e32 v5, 0xffff0000, v3
	v_pk_mul_f32 v[6:7], v[50:51], v[6:7]
	s_nop 0
	v_pk_fma_f32 v[4:5], v[14:15], v[4:5], v[6:7]
	v_lshlrev_b32_e32 v6, 16, v11
	v_and_b32_e32 v7, 0xffff0000, v11
	v_pk_fma_f32 v[4:5], v[58:59], v[6:7], v[4:5]
	s_nop 0
	v_cvt_pk_f16_f32 v3, v4, v5
	v_add_co_u32_e32 v4, vcc, 0x2b600000, v42
	s_nop 1
	v_addc_co_u32_e32 v5, vcc, 0, v43, vcc
	global_store_dwordx4 v[4:5], v[0:3], off offset:2048
	s_and_saveexec_b64 s[14:15], s[4:5]
	s_cbranch_execz .LBB0_455
	v_add_co_u32_e32 v0, vcc, 0x21600000, v42
	v_mov_b32_e32 v8, 0
	s_nop 0
	v_addc_co_u32_e32 v1, vcc, 0, v43, vcc
	global_load_dwordx4 v[4:7], v[0:1], off offset:3072
	v_mov_b32_e32 v0, 0
	s_and_b64 vcc, exec, s[10:11]
	v_mov_b32_e32 v9, 0
	v_mov_b32_e32 v10, 0
	v_mov_b32_e32 v11, 0
	s_cbranch_vccnz .LBB0_472
	global_load_dwordx4 v[8:11], v17, s[28:29] offset:3072

; __device__ __forceinline__ float fexp(float x) { return __builtin_amdgcn_exp2f(x * 1.44269504089f); }
; __device__ __forceinline__ float fsigmoid(float x) { return __builtin_amdgcn_rcpf(1.0f + fexp(-x)); }
; __device__ __forceinline__ float shfl_xor_(float v, int m) { return __builtin_bit_cast(float, __builtin_amdgcn_ds_bpermute((lane_id() ^ m) << 2, __builtin_bit_cast(int, v))); }
; __device__ __forceinline__ void phase_rwkv_pre(const Frame& F, const Args& a, int l) {
;     ...
;             const v4u cur = *(const v4u*)(CF + (size_t)t * 2048 + cb);
;             const v4u prv = hp ? *(const v4u*)(CF + (size_t)(t - 1) * 2048 + cb) : zc;
;             const v4u nxt = hn ? *(const v4u*)(CF + (size_t)(t + 1) * 2048 + cb) : zc;
;             float o[8];
; #pragma unroll
;             for (int q = 0; q < 4; ++q) {
;                 const unsigned wc_ = cur[q], wp = prv[q], wn = nxt[q];
;                 const int c = cb + 2 * q;
;                 o[2 * q] = cw[c] * bf_lo(wp) + cw[1920 + c] * bf_lo(wc_) + cw[3840 + c] * bf_lo(wn);
;                 o[2 * q + 1] = cw[c + 1] * bf_hi(wp) + cw[1920 + c + 1] * bf_hi(wc_) + cw[3840 + c + 1] * bf_hi(wn);
;             }
;             if (j < 3) {
;                 v4u w; w.x = pkh2(o[0], o[1]); w.y = pkh2(o[2], o[3]); w.z = pkh2(o[4], o[5]); w.w = pkh2(o[6], o[7]);
;                 *(v4u*)(RK + (size_t)t * 2048 + cb) = w;
;                 if (j == 1) {
;                     float kv[8]; float ss = 0.f;
; #pragma unroll
;                     for (int e = 0; e < 8; ++e) { kv[e] = o[e] * kk_w[8 * lane + e]; ss += kv[e] * kv[e]; }
;                     ss += shfl_xor_(ss, 1); ss += shfl_xor_(ss, 2); ss += shfl_xor_(ss, 4);
;                     const float rn = 1.0f / sqrtf(ss + 1e-12f);
;                     v4u w2; w2.x = pkh2(kv[0] * rn, kv[1] * rn); w2.y = pkh2(kv[2] * rn, kv[3] * rn); w2.z = pkh2(kv[4] * rn, kv[5] * rn); w2.w = pkh2(kv[6] * rn, kv[7] * rn);
;                     *(v4u*)(RK + (size_t)t * 2048 + 1536 + 8 * lane) = w2;
;                 }
;             } else {
;                 if (lane < 16) {
; #pragma unroll
;                     for (int e = 0; e < 8; ++e) { const float ex = fexp(2.0f * o[e]); o[e] = 1.0f - 2.0f / (ex + 1.0f); }
;                 } else if (lane >= 32) {
; #pragma unroll
;                     for (int e = 0; e < 8; ++e) o[e] = fsigmoid(o[e]);
;                 }
.LBB0_474:
	s_waitcnt vmcnt(0)
	s_nop 1
	v_mov_b32_e32 v42, v156
	v_mov_b32_e32 v43, v157
	v_mov_b32_e32 v44, v158
	v_mov_b32_e32 v45, v159
	s_nop 1
	v_mov_b32_e32 v12, v160
	v_mov_b32_e32 v13, v161
	v_mov_b32_e32 v14, v162
	v_mov_b32_e32 v15, v163
	s_nop 1
	v_mov_b32_e32 v46, v164
	v_mov_b32_e32 v47, v165
	v_mov_b32_e32 v48, v166
	v_mov_b32_e32 v49, v167
	s_nop 1
	v_mov_b32_e32 v50, v168
	v_mov_b32_e32 v51, v169
	v_mov_b32_e32 v52, v170
	v_mov_b32_e32 v53, v171
	v_lshlrev_b32_e32 v56, 16, v4
	v_and_b32_e32 v57, 0xffff0000, v4
	v_lshlrev_b32_e32 v54, 16, v8
	v_and_b32_e32 v55, 0xffff0000, v8
	v_lshlrev_b32_e32 v4, 16, v5
	v_and_b32_e32 v5, 0xffff0000, v5
	v_lshlrev_b32_e32 v8, 16, v9
	v_and_b32_e32 v9, 0xffff0000, v9
	s_waitcnt vmcnt(0)
	v_pk_mul_f32 v[50:51], v[50:51], v[56:57]
	s_nop 0
	v_pk_fma_f32 v[12:13], v[12:13], v[54:55], v[50:51]
	v_pk_mul_f32 v[4:5], v[52:53], v[4:5]
	v_lshlrev_b32_e32 v50, 16, v0
	v_and_b32_e32 v51, 0xffff0000, v0
	v_pk_fma_f32 v[4:5], v[14:15], v[8:9], v[4:5]
	v_lshlrev_b32_e32 v0, 16, v1
	v_and_b32_e32 v1, 0xffff0000, v1
	v_lshlrev_b32_e32 v8, 16, v6
	v_and_b32_e32 v9, 0xffff0000, v6
	v_pk_mul_f32 v[8:9], v[46:47], v[8:9]
	v_lshlrev_b32_e32 v6, 16, v7
	v_and_b32_e32 v7, 0xffff0000, v7
	v_pk_mul_f32 v[6:7], v[48:49], v[6:7]
	s_nop 1
	v_mov_b32_e32 v54, v172
	v_mov_b32_e32 v55, v173
	v_mov_b32_e32 v56, v174
	v_mov_b32_e32 v57, v175
	s_nop 1
	v_mov_b32_e32 v58, v176
	v_mov_b32_e32 v59, v177
	v_mov_b32_e32 v60, v178
	v_mov_b32_e32 v61, v179
	v_pk_fma_f32 v[0:1], v[60:61], v[0:1], v[4:5]
	v_lshlrev_b32_e32 v4, 16, v10
	v_and_b32_e32 v5, 0xffff0000, v10
	v_pk_fma_f32 v[4:5], v[42:43], v[4:5], v[8:9]
	v_lshlrev_b32_e32 v8, 16, v2
	v_and_b32_e32 v9, 0xffff0000, v2
	v_pk_fma_f32 v[4:5], v[54:55], v[8:9], v[4:5]
	v_lshlrev_b32_e32 v8, 16, v11
	v_and_b32_e32 v9, 0xffff0000, v11
	v_pk_fma_f32 v[6:7], v[44:45], v[8:9], v[6:7]
	v_lshlrev_b32_e32 v2, 16, v3
	v_and_b32_e32 v3, 0xffff0000, v3
	v_pk_fma_f32 v[12:13], v[58:59], v[50:51], v[12:13]
	v_pk_fma_f32 v[6:7], v[56:57], v[2:3], v[6:7]
	s_and_saveexec_b64 s[10:11], s[6:7]
	s_xor_b64 s[10:11], exec, s[10:11]
	s_cbranch_execz .LBB0_478
	s_and_saveexec_b64 s[12:13], s[8:9]
	s_cbranch_execz .LBB0_477
	v_mul_f32_e32 v2, 0xbfb8aa3b, v12
	v_exp_f32_e32 v2, v2
	v_mul_f32_e32 v3, 0xbfb8aa3b, v13
	v_exp_f32_e32 v3, v3
	v_mul_f32_e32 v0, 0xbfb8aa3b, v0
	v_add_f32_e32 v2, 1.0, v2
	v_rcp_f32_e32 v12, v2
	v_add_f32_e32 v3, 1.0, v3
	v_mul_f32_e32 v2, 0xbfb8aa3b, v4
	v_rcp_f32_e32 v13, v3
	v_exp_f32_e32 v2, v2
	v_mul_f32_e32 v3, 0xbfb8aa3b, v5
	v_exp_f32_e32 v3, v3
	v_mul_f32_e32 v1, 0xbfb8aa3b, v1
	v_add_f32_e32 v2, 1.0, v2
	v_rcp_f32_e32 v4, v2
	v_add_f32_e32 v2, 1.0, v3
	v_mul_f32_e32 v3, 0xbfb8aa3b, v6
	v_exp_f32_e32 v3, v3
	v_mul_f32_e32 v5, 0xbfb8aa3b, v7
	v_exp_f32_e32 v0, v0
	v_exp_f32_e32 v1, v1
	v_exp_f32_e32 v7, v5
	v_rcp_f32_e32 v5, v2
	v_add_f32_e32 v2, 1.0, v3
	v_add_f32_e32 v0, 1.0, v0
	v_add_f32_e32 v1, 1.0, v1
	v_rcp_f32_e32 v6, v2
	v_add_f32_e32 v2, 1.0, v7
	v_rcp_f32_e32 v0, v0
	v_rcp_f32_e32 v1, v1
	v_rcp_f32_e32 v7, v2

; __device__ __forceinline__ void phase_rwkv_post(const Frame& F, const Args& a, int l) {
;     const unsigned short* EA = (const unsigned short*)(F.ws + WS_AR + AR_EA); const unsigned short* RK = (const unsigned short*)(F.ws + WS_AR + AR_RKVK);
;     const bf16* GT = (const bf16*)(F.ws + WS_AR + AR_GT); const float* YS = (const float*)(F.ws + WS_AR + AR_YS); const bf16* YSB = (const bf16*)(F.ws + WS_AR + AR_YSB); bf16* YC = (bf16*)(F.ws + WS_AR + AR_YC); (void)YS; (void)YSB;
;     const float* k_a = a.in[F.z + 17] + (size_t)l * 512; const float* r_k = a.in[F.z + 18] + (size_t)l * 512; const float* ln_w = a.in[F.z + 19] + (size_t)l * 512; const float* ln_b = a.in[F.z + 20] + (size_t)l * 512;
;     const int lane = F.lane, c0 = 8 * lane;
;     for (int t = F.gw; t < T; t += F.NGW) {
;         float y[8];
;     ...
;         { const v4u p = *(const v4u*)(YSB + (size_t)t * 512 + c0), q = *(const v4u*)(YSB + ((size_t)T + t) * 512 + c0);
; #pragma unroll
;           for (int i = 0; i < 4; ++i) { y[2 * i] = bf_lo(p[i]) + bf_lo(q[i]); y[2 * i + 1] = bf_hi(p[i]) + bf_hi(q[i]); } }
;     ...
;         { const f32x4 p0 = *(const f32x4*)(YS + (size_t)t * 512 + c0), p1 = *(const f32x4*)(YS + (size_t)t * 512 + c0 + 4);
;           const f32x4 q0 = *(const f32x4*)(YS + ((size_t)T + t) * 512 + c0), q1 = *(const f32x4*)(YS + ((size_t)T + t) * 512 + c0 + 4);
;           y[0] = p0.x + q0.x; y[1] = p0.y + q0.y; y[2] = p0.z + q0.z; y[3] = p0.w + q0.w; y[4] = p1.x + q1.x; y[5] = p1.y + q1.y; y[6] = p1.z + q1.z; y[7] = p1.w + q1.w; }
;     ...
;         const v4u rr = *(const v4u*)(RK + (size_t)t * 2048 + c0), kk = *(const v4u*)(RK + (size_t)t * 2048 + 512 + c0), vv = *(const v4u*)(RK + (size_t)t * 2048 + 1024 + c0);
;         const v4u a0 = *(const v4u*)(EA + (size_t)t * 2048 + 1024 + c0), a1 = *(const v4u*)(EA + (size_t)t * 2048 + 1536 + c0);
;         const v4u gg = *(const v4u*)(GT + (size_t)t * 512 + c0);
;         float r[8], k[8], v[8], aa0[8], aa1[8], g[8];
; #pragma unroll
;         for (int q = 0; q < 4; ++q) { r[2 * q] = h_lo(rr[q]); r[2 * q + 1] = h_hi(rr[q]); k[2 * q] = h_lo(kk[q]); k[2 * q + 1] = h_hi(kk[q]); v[2 * q] = h_lo(vv[q]); v[2 * q + 1] = h_hi(vv[q]);
;             aa0[2 * q] = h_lo(a0[q]); aa0[2 * q + 1] = h_hi(a0[q]); aa1[2 * q] = h_lo(a1[q]); aa1[2 * q + 1] = h_hi(a1[q]); g[2 * q] = bf_lo(gg[q]); g[2 * q + 1] = bf_hi(gg[q]); }
;         float s = 0.f, bon = 0.f;
; #pragma unroll
.LBB0_829:
	s_cmp_ge_i32 s50, s74
	s_cselect_b64 s[6:7], -1, 0
	s_and_b64 s[4:5], s[6:7], s[44:45]
	s_andn2_b64 vcc, exec, s[4:5]
	s_cbranch_vccnz .LBB0_833
	s_mov_b32 s12, 0
	v_mbcnt_lo_u32_b32 v0, -1, 0
	v_mbcnt_hi_u32_b32 v0, -1, v0
	v_readlane_b32 s4, v254, 5
	v_readlane_b32 s14, v254, 1
	v_readlane_b32 s15, v254, 2
	v_add_u32_e32 v0, s4, v0
	s_load_dwordx2 s[4:5], s[14:15], 0xf8
	s_waitcnt lgkmcnt(0)
	v_readlane_b32 s11, v254, 0
	v_readfirstlane_b32 s8, v0
	v_readlane_b32 s13, v254, 10
	s_mov_b32 s9, s13
	s_mov_b32 s10, s11
	s_ashr_i32 s8, s8, 6
	s_lshl_b32 s10, s10, 3
	s_add_i32 s8, s10, s8
	s_load_dwordx2 s[10:11], s[14:15], 0xf0
	s_waitcnt lgkmcnt(0)
	s_cmp_gt_i32 s8, 0x9fff
	s_cbranch_scc1 .LBB0_833
	s_ashr_i32 s13, s12, 31
	s_lshl_b32 s10, s9, 3
	s_lshl_b64 s[12:13], s[12:13], 3
	v_readlane_b32 s14, v254, 1
	v_readlane_b32 s15, v254, 2
	s_add_u32 s20, s14, s12
	s_addc_u32 s21, s15, s13
	s_load_dwordx8 s[12:19], s[20:21], 0x88
	v_readlane_b32 s20, v254, 34
	v_readlane_b32 s21, v254, 35
	s_lshl_b64 s[20:21], s[20:21], 2
	v_lshlrev_b32_e32 v1, 5, v0
	s_waitcnt lgkmcnt(0)
	s_add_u32 s18, s18, s20
	s_addc_u32 s19, s19, s21
	s_add_u32 s16, s16, s20
	s_addc_u32 s17, s17, s21
	s_add_u32 s14, s14, s20
	s_addc_u32 s15, s15, s21
	s_add_u32 s12, s12, s20
	v_and_b32_e32 v184, 0x7e0, v1
	s_addc_u32 s13, s13, s21
	s_ashr_i32 s9, s8, 31
	s_waitcnt vmcnt(0)
	v_lshl_add_u64 v[12:13], s[12:13], 0, v[184:185]
	s_lshl_b64 s[12:13], s[8:9], 12
	s_add_u32 s12, s4, s12
	s_addc_u32 s13, s5, s13
	s_ashr_i32 s11, s10, 31
	v_lshl_add_u64 v[14:15], s[14:15], 0, v[184:185]
	v_lshl_add_u64 v[16:17], s[16:17], 0, v[184:185]
	s_lshl_b64 s[14:15], s[10:11], 12
	s_lshl_b64 s[16:17], s[8:9], 10
	v_and_b32_e32 v0, 63, v0
	s_add_u32 s16, s4, s16
	v_lshl_add_u64 v[18:19], s[18:19], 0, v[184:185]
	v_lshlrev_b32_e32 v184, 4, v0
	s_addc_u32 s17, s5, s17
	s_lshl_b64 s[18:19], s[10:11], 10
	global_load_dwordx4 v[96:99], v[12:13], off offset:16
	global_load_dwordx4 v[100:103], v[12:13], off
	global_load_dwordx4 v[104:107], v[14:15], off offset:16
	global_load_dwordx4 v[108:111], v[14:15], off
	global_load_dwordx4 v[112:115], v[16:17], off offset:16
	global_load_dwordx4 v[116:119], v[16:17], off
	global_load_dwordx4 v[120:123], v[18:19], off offset:16
	global_load_dwordx4 v[124:127], v[18:19], off
.LBB0_832:
	v_lshl_add_u64 v[20:21], s[16:17], 0, v[184:185]
	v_add_co_u32_e32 v0, vcc, 0x19e00000, v20
	v_lshl_add_u64 v[30:31], s[12:13], 0, v[184:185]
	s_nop 0
	v_addc_co_u32_e32 v1, vcc, 0, v21, vcc
	v_add_co_u32_e32 v4, vcc, 0x1c600000, v20
	global_load_dwordx4 v[0:3], v[0:1], off
	s_nop 0
	v_addc_co_u32_e32 v5, vcc, 0, v21, vcc
	v_add_co_u32_e32 v8, vcc, s68, v30
	global_load_dwordx4 v[4:7], v[4:5], off
	s_nop 0
	v_addc_co_u32_e32 v9, vcc, 0, v31, vcc
	global_load_dwordx4 v[22:25], v[8:9], off
	global_load_dwordx4 v[26:29], v[8:9], off offset:1024
	s_nop 0
	global_load_dwordx4 v[8:11], v[8:9], off offset:2048
	s_mov_b32 s4, 0x37600000
	v_add_co_u32_e32 v34, vcc, s4, v30
	s_mov_b32 s4, 0x41600000
	s_nop 0
	v_addc_co_u32_e32 v35, vcc, 0, v31, vcc
	global_load_dwordx4 v[30:33], v[34:35], off offset:2048
	s_nop 0
	global_load_dwordx4 v[34:37], v[34:35], off offset:3072
	v_add_co_u32_e32 v38, vcc, s4, v20
	s_add_i32 s8, s8, s10
	s_nop 0
	v_addc_co_u32_e32 v39, vcc, 0, v21, vcc
	global_load_dwordx4 v[38:41], v[38:39], off
	s_nop 0
	s_add_u32 s12, s12, s14
	s_addc_u32 s13, s13, s15
	s_add_u32 s16, s16, s18
	s_addc_u32 s17, s17, s19
	s_cmp_lt_i32 s8, 0xa000
	s_waitcnt vmcnt(5)
	s_nop 1
	v_mov_b32_e32 v42, v96
	v_mov_b32_e32 v43, v97
	v_mov_b32_e32 v44, v98
	v_mov_b32_e32 v45, v99
	s_nop 1
	v_mov_b32_e32 v46, v100
	v_mov_b32_e32 v47, v101
	v_mov_b32_e32 v48, v102
	v_mov_b32_e32 v49, v103
	v_cvt_f32_f16_e32 v50, v22
	v_cvt_f32_f16_sdwa v51, v22 dst_sel:DWORD dst_unused:UNUSED_PAD src0_sel:WORD_1
	s_waitcnt vmcnt(4)
	v_cvt_f32_f16_e32 v52, v26
	v_cvt_f32_f16_sdwa v53, v26 dst_sel:DWORD dst_unused:UNUSED_PAD src0_sel:WORD_1
	v_cvt_f32_f16_e32 v26, v27
	v_cvt_f32_f16_sdwa v27, v27 dst_sel:DWORD dst_unused:UNUSED_PAD src0_sel:WORD_1
	v_pk_mul_f32 v[62:63], v[50:51], v[52:53]
	s_waitcnt vmcnt(2)
	s_nop 1
	v_mov_b32_e32 v50, v104
	v_mov_b32_e32 v51, v105
	v_mov_b32_e32 v52, v106
	v_mov_b32_e32 v53, v107
	s_nop 1
	v_mov_b32_e32 v54, v108
	v_mov_b32_e32 v55, v109
	v_mov_b32_e32 v56, v110
	v_mov_b32_e32 v57, v111
	v_cvt_f32_f16_e32 v58, v30
	v_cvt_f32_f16_sdwa v59, v30 dst_sel:DWORD dst_unused:UNUSED_PAD src0_sel:WORD_1
	s_waitcnt vmcnt(1)
	v_cvt_f32_f16_e32 v60, v34
	v_cvt_f32_f16_sdwa v61, v34 dst_sel:DWORD dst_unused:UNUSED_PAD src0_sel:WORD_1
	v_cvt_f32_f16_e32 v30, v31
	v_pk_add_f32 v[58:59], v[58:59], -1.0 op_sel_hi:[1,0]
	v_cvt_f32_f16_sdwa v31, v31 dst_sel:DWORD dst_unused:UNUSED_PAD src0_sel:WORD_1
	v_pk_add_f32 v[60:61], v[60:61], -1.0 op_sel_hi:[1,0]
	s_waitcnt vmcnt(0)
	v_pk_fma_f32 v[58:59], v[46:47], v[58:59], 1.0 op_sel_hi:[1,1,0]
	v_pk_fma_f32 v[46:47], v[46:47], v[60:61], 1.0 op_sel_hi:[1,1,0]
	v_cvt_f32_f16_e32 v34, v35
	v_pk_add_f32 v[46:47], v[58:59], v[46:47]
	v_cvt_f32_f16_sdwa v35, v35 dst_sel:DWORD dst_unused:UNUSED_PAD src0_sel:WORD_1
	s_waitcnt vmcnt(0)
; __device__ __forceinline__ float shfl_xor_(float v, int m) { return __builtin_bit_cast(float, __builtin_amdgcn_ds_bpermute((lane_id() ^ m) << 2, __builtin_bit_cast(int, v))); }
; __device__ __forceinline__ void phase_rwkv_post(const Frame& F, const Args& a, int l) {
;     ...
;         float s = 0.f, bon = 0.f;
; #pragma unroll
;         for (int e = 0; e < 8; ++e) { s += y[e]; const float kaa = k_a[c0 + e]; bon += r[e] * k[e] * r_k[c0 + e] * ((1.0f + (aa0[e] - 1.0f) * kaa) + (1.0f + (aa1[e] - 1.0f) * kaa)); }
;         s += shfl_xor_(s, 1); s += shfl_xor_(s, 2); s += shfl_xor_(s, 4);
;         bon += shfl_xor_(bon, 1); bon += shfl_xor_(bon, 2); bon += shfl_xor_(bon, 4);
	v_pk_mul_f32 v[54:55], v[62:63], v[54:55]
	s_nop 0
	v_pk_mul_f32 v[46:47], v[54:55], v[46:47]
	v_lshlrev_b32_e32 v54, 16, v0
	v_add_f32_e32 v22, 0, v46
	v_add_f32_e32 v46, v22, v47
	v_cvt_f32_f16_e32 v22, v23
	v_cvt_f32_f16_sdwa v23, v23 dst_sel:DWORD dst_unused:UNUSED_PAD src0_sel:WORD_1
	v_cvt_f32_f16_sdwa v47, v11 dst_sel:DWORD dst_unused:UNUSED_PAD src0_sel:WORD_1
	v_and_b32_e32 v55, 0xffff0000, v0
	v_lshlrev_b32_e32 v0, 16, v4
	v_pk_mul_f32 v[22:23], v[22:23], v[26:27]
	v_pk_add_f32 v[26:27], v[30:31], -1.0 op_sel_hi:[1,0]
	v_pk_add_f32 v[30:31], v[34:35], -1.0 op_sel_hi:[1,0]
	v_pk_fma_f32 v[26:27], v[26:27], v[48:49], 1.0 op_sel_hi:[1,1,0]
	v_pk_fma_f32 v[30:31], v[30:31], v[48:49], 1.0 op_sel_hi:[1,1,0]
	v_pk_mul_f32 v[22:23], v[22:23], v[56:57]
	v_pk_add_f32 v[26:27], v[26:27], v[30:31]
	v_cvt_f32_f16_e32 v30, v32
	v_pk_mul_f32 v[22:23], v[22:23], v[26:27]
	v_cvt_f32_f16_e32 v26, v28
	v_add_f32_e32 v22, v46, v22
	v_add_f32_e32 v46, v22, v23
	v_cvt_f32_f16_e32 v22, v24
	v_cvt_f32_f16_sdwa v23, v24 dst_sel:DWORD dst_unused:UNUSED_PAD src0_sel:WORD_1
	v_cvt_f32_f16_sdwa v27, v28 dst_sel:DWORD dst_unused:UNUSED_PAD src0_sel:WORD_1
	v_cvt_f32_f16_sdwa v31, v32 dst_sel:DWORD dst_unused:UNUSED_PAD src0_sel:WORD_1
	v_cvt_f32_f16_e32 v34, v36
	v_cvt_f32_f16_sdwa v35, v36 dst_sel:DWORD dst_unused:UNUSED_PAD src0_sel:WORD_1
	v_pk_mul_f32 v[22:23], v[22:23], v[26:27]
	v_pk_add_f32 v[26:27], v[30:31], -1.0 op_sel_hi:[1,0]
	v_pk_mul_f32 v[22:23], v[22:23], v[50:51]
	v_pk_add_f32 v[30:31], v[34:35], -1.0 op_sel_hi:[1,0]
	v_pk_fma_f32 v[26:27], v[26:27], v[42:43], 1.0 op_sel_hi:[1,1,0]
	v_pk_fma_f32 v[30:31], v[30:31], v[42:43], 1.0 op_sel_hi:[1,1,0]
	v_cvt_f32_f16_e32 v24, v29
	v_pk_add_f32 v[26:27], v[26:27], v[30:31]
	v_cvt_f32_f16_e32 v28, v37
	v_pk_mul_f32 v[22:23], v[22:23], v[26:27]
	v_cvt_f32_f16_e32 v26, v33
	v_add_f32_e32 v22, v46, v22
	v_add_f32_e32 v30, v22, v23
	v_cvt_f32_f16_e32 v22, v25
	v_cvt_f32_f16_sdwa v23, v25 dst_sel:DWORD dst_unused:UNUSED_PAD src0_sel:WORD_1
	v_cvt_f32_f16_sdwa v25, v29 dst_sel:DWORD dst_unused:UNUSED_PAD src0_sel:WORD_1
	v_cvt_f32_f16_sdwa v27, v33 dst_sel:DWORD dst_unused:UNUSED_PAD src0_sel:WORD_1
	v_cvt_f32_f16_sdwa v29, v37 dst_sel:DWORD dst_unused:UNUSED_PAD src0_sel:WORD_1
	v_cvt_f32_f16_e32 v46, v11
	v_pk_mul_f32 v[22:23], v[22:23], v[24:25]
	v_pk_add_f32 v[24:25], v[26:27], -1.0 op_sel_hi:[1,0]
	v_pk_add_f32 v[26:27], v[28:29], -1.0 op_sel_hi:[1,0]
	v_pk_fma_f32 v[24:25], v[24:25], v[44:45], 1.0 op_sel_hi:[1,1,0]
	v_pk_fma_f32 v[26:27], v[26:27], v[44:45], 1.0 op_sel_hi:[1,1,0]
	v_pk_mul_f32 v[22:23], v[22:23], v[52:53]
	v_pk_add_f32 v[24:25], v[24:25], v[26:27]
	v_lshlrev_b32_e32 v48, 16, v41
	v_pk_mul_f32 v[22:23], v[22:23], v[24:25]
	v_lshlrev_b32_e32 v24, 16, v7
	v_add_f32_e32 v22, v30, v22
	v_add_f32_e32 v22, v22, v23
	v_mbcnt_lo_u32_b32 v23, -1, 0
	v_mbcnt_hi_u32_b32 v23, -1, v23
	v_and_b32_e32 v25, 0xffff0000, v7
	v_lshlrev_b32_e32 v23, 2, v23
	v_xor_b32_e32 v43, 4, v23
	v_mbcnt_lo_u32_b32 v23, -1, 0
	v_mbcnt_hi_u32_b32 v23, -1, v23
	v_and_b32_e32 v49, 0xffff0000, v41
	v_lshlrev_b32_e32 v23, 2, v23
	v_xor_b32_e32 v56, 8, v23
	v_mbcnt_lo_u32_b32 v23, -1, 0
	v_mbcnt_hi_u32_b32 v23, -1, v23
	v_cvt_f32_f16_sdwa v7, v10 dst_sel:DWORD dst_unused:UNUSED_PAD src0_sel:WORD_1
	v_lshlrev_b32_e32 v23, 2, v23
	v_xor_b32_e32 v57, 16, v23
	v_mbcnt_lo_u32_b32 v23, -1, 0
	v_mbcnt_hi_u32_b32 v23, -1, v23
	v_and_b32_e32 v11, 0xffff0000, v40
	v_lshlrev_b32_e32 v23, 2, v23
	v_xor_b32_e32 v23, 4, v23
	ds_bpermute_b32 v23, v23, v22
	v_and_b32_e32 v41, 0xffff0000, v1
	v_lshlrev_b32_e32 v50, 16, v5
	v_and_b32_e32 v51, 0xffff0000, v5
	v_cvt_f32_f16_sdwa v5, v8 dst_sel:DWORD dst_unused:UNUSED_PAD src0_sel:WORD_1
	s_waitcnt lgkmcnt(0)
	v_add_f32_e32 v22, v22, v23
	v_mbcnt_lo_u32_b32 v23, -1, 0
	v_mbcnt_hi_u32_b32 v23, -1, v23
	v_lshlrev_b32_e32 v52, 16, v39
	v_lshlrev_b32_e32 v23, 2, v23
	v_xor_b32_e32 v23, 8, v23
	ds_bpermute_b32 v23, v23, v22
	v_and_b32_e32 v53, 0xffff0000, v39
	s_waitcnt lgkmcnt(0)
	v_add_f32_e32 v22, v22, v23
	v_mbcnt_lo_u32_b32 v23, -1, 0
	v_mbcnt_hi_u32_b32 v23, -1, v23
	s_nop 0
	v_lshlrev_b32_e32 v23, 2, v23
	v_xor_b32_e32 v23, 16, v23
	ds_bpermute_b32 v23, v23, v22
	s_waitcnt lgkmcnt(0)
; __device__ __forceinline__ unsigned pk2(float lo, float hi) { return cvt_pk_bf16(lo, hi); }
; __device__ __forceinline__ float shfl_xor_(float v, int m) { return __builtin_bit_cast(float, __builtin_amdgcn_ds_bpermute((lane_id() ^ m) << 2, __builtin_bit_cast(int, v))); }
; __device__ __forceinline__ void phase_rwkv_post(const Frame& F, const Args& a, int l) {
;     ...
;         float s = 0.f, bon = 0.f;
; #pragma unroll
;         for (int e = 0; e < 8; ++e) { s += y[e]; const float kaa = k_a[c0 + e]; bon += r[e] * k[e] * r_k[c0 + e] * ((1.0f + (aa0[e] - 1.0f) * kaa) + (1.0f + (aa1[e] - 1.0f) * kaa)); }
;         s += shfl_xor_(s, 1); s += shfl_xor_(s, 2); s += shfl_xor_(s, 4);
;         bon += shfl_xor_(bon, 1); bon += shfl_xor_(bon, 2); bon += shfl_xor_(bon, 4);
;         const float mu = s * (1.0f / 64.0f); float q2 = 0.f;
; #pragma unroll
;         for (int e = 0; e < 8; ++e) { const float d_ = y[e] - mu; q2 += d_ * d_; }
;         q2 += shfl_xor_(q2, 1); q2 += shfl_xor_(q2, 2); q2 += shfl_xor_(q2, 4);
;         const float rstd = 1.0f / sqrtf(q2 * (1.0f / 64.0f) + 64e-5f);
;         float o[8];
; #pragma unroll
;         for (int e = 0; e < 8; ++e) o[e] = (((y[e] - mu) * rstd) * ln_w[c0 + e] + ln_b[c0 + e] + bon * v[e]) * g[e];
;         v4u w; w.x = pk2(o[0], o[1]); w.y = pk2(o[2], o[3]); w.z = pk2(o[4], o[5]); w.w = pk2(o[6], o[7]);
;         *(v4u*)(YC + (size_t)t * 512 + c0) = w;
	v_add_f32_e32 v42, v22, v23
	v_mbcnt_lo_u32_b32 v22, -1, 0
	v_mbcnt_hi_u32_b32 v22, -1, v22
	v_and_b32_e32 v23, 0xffff0000, v3
	v_lshlrev_b32_e32 v22, 2, v22
	v_xor_b32_e32 v60, 4, v22
	v_mbcnt_lo_u32_b32 v22, -1, 0
	v_mbcnt_hi_u32_b32 v22, -1, v22
	s_nop 0
	v_lshlrev_b32_e32 v22, 2, v22
	v_xor_b32_e32 v61, 8, v22
	v_mbcnt_lo_u32_b32 v22, -1, 0
	v_mbcnt_hi_u32_b32 v22, -1, v22
	s_nop 0
	v_lshlrev_b32_e32 v22, 2, v22
	v_xor_b32_e32 v62, 16, v22
	v_lshlrev_b32_e32 v22, 16, v3
	v_pk_add_f32 v[44:45], v[22:23], v[24:25]
	v_lshlrev_b32_e32 v22, 16, v2
	v_and_b32_e32 v23, 0xffff0000, v2
	v_lshlrev_b32_e32 v2, 16, v6
	v_and_b32_e32 v3, 0xffff0000, v6
	v_cvt_f32_f16_e32 v6, v10
	v_lshlrev_b32_e32 v10, 16, v40
	v_lshlrev_b32_e32 v40, 16, v1
	v_and_b32_e32 v1, 0xffff0000, v4
	v_pk_add_f32 v[0:1], v[54:55], v[0:1]
	v_pk_add_f32 v[40:41], v[40:41], v[50:51]
	v_cvt_f32_f16_e32 v50, v9
	v_cvt_f32_f16_sdwa v51, v9 dst_sel:DWORD dst_unused:UNUSED_PAD src0_sel:WORD_1
	v_cvt_f32_f16_e32 v4, v8
	v_lshlrev_b32_e32 v8, 16, v38
	v_and_b32_e32 v9, 0xffff0000, v38
	v_add_f32_e32 v38, 0, v0
	v_add_f32_e32 v38, v1, v38
	v_add_f32_e32 v38, v40, v38
	v_pk_add_f32 v[2:3], v[22:23], v[2:3]
	v_add_f32_e32 v38, v41, v38
	s_nop 1
	v_mov_b32_e32 v22, v112
	v_mov_b32_e32 v23, v113
	v_mov_b32_e32 v24, v114
	v_mov_b32_e32 v25, v115
	s_nop 1
	v_mov_b32_e32 v26, v116
	v_mov_b32_e32 v27, v117
	v_mov_b32_e32 v28, v118
	v_mov_b32_e32 v29, v119
	s_nop 1
	v_mov_b32_e32 v30, v120
	v_mov_b32_e32 v31, v121
	v_mov_b32_e32 v32, v122
	v_mov_b32_e32 v33, v123
	s_nop 1
	v_mov_b32_e32 v34, v124
	v_mov_b32_e32 v35, v125
	v_mov_b32_e32 v36, v126
	v_mov_b32_e32 v37, v127
	v_add_f32_e32 v38, v2, v38
	v_add_f32_e32 v38, v3, v38
	v_add_f32_e32 v38, v44, v38
	v_add_f32_e32 v38, v45, v38
	ds_bpermute_b32 v39, v43, v38
	s_waitcnt lgkmcnt(0)
	v_add_f32_e32 v38, v38, v39
	ds_bpermute_b32 v39, v56, v38
	s_waitcnt lgkmcnt(0)
	v_add_f32_e32 v38, v38, v39
	ds_bpermute_b32 v39, v57, v38
	s_waitcnt lgkmcnt(0)
	v_add_f32_e32 v38, v38, v39
	v_mul_f32_e32 v38, 0x3c800000, v38
	v_pk_add_f32 v[0:1], v[0:1], v[38:39] op_sel_hi:[1,0] neg_lo:[0,1] neg_hi:[0,1]
	v_pk_add_f32 v[40:41], v[40:41], v[38:39] op_sel_hi:[1,0] neg_lo:[0,1] neg_hi:[0,1]
	v_pk_mul_f32 v[54:55], v[0:1], v[0:1]
	v_pk_mul_f32 v[56:57], v[40:41], v[40:41]
	v_add_f32_e32 v43, v54, v55
	v_pk_add_f32 v[2:3], v[2:3], v[38:39] op_sel_hi:[1,0] neg_lo:[0,1] neg_hi:[0,1]
	v_add_f32_e32 v43, v56, v43
	v_pk_mul_f32 v[58:59], v[2:3], v[2:3]
	v_add_f32_e32 v43, v57, v43
	v_pk_add_f32 v[38:39], v[44:45], v[38:39] op_sel_hi:[1,0] neg_lo:[0,1] neg_hi:[0,1]
	v_add_f32_e32 v43, v58, v43
	v_pk_mul_f32 v[44:45], v[38:39], v[38:39]
	v_add_f32_e32 v43, v59, v43
	v_add_f32_e32 v43, v44, v43
	v_add_f32_e32 v43, v45, v43
	ds_bpermute_b32 v44, v60, v43
	s_waitcnt lgkmcnt(0)
	v_add_f32_e32 v43, v43, v44
	ds_bpermute_b32 v44, v61, v43
	s_waitcnt lgkmcnt(0)
	v_add_f32_e32 v43, v43, v44
	ds_bpermute_b32 v44, v62, v43
	s_waitcnt lgkmcnt(0)
	v_add_f32_e32 v43, v43, v44
	v_fmamk_f32 v43, v43, 0x3c800000, v252
	v_cmp_gt_f32_e32 vcc, s86, v43
	v_mul_f32_e32 v44, 0x4f800000, v43
	s_nop 0
	v_cndmask_b32_e32 v43, v43, v44, vcc
	v_sqrt_f32_e32 v44, v43
	s_nop 0
	v_add_u32_e32 v45, -1, v44
	v_fma_f32 v54, -v45, v44, v43
	v_cmp_ge_f32_e64 s[4:5], 0, v54
	v_add_u32_e32 v54, 1, v44
	s_nop 0
	v_cndmask_b32_e64 v45, v44, v45, s[4:5]
	v_fma_f32 v44, -v54, v44, v43
	v_cmp_lt_f32_e64 s[4:5], 0, v44
	s_nop 1
	v_cndmask_b32_e64 v44, v45, v54, s[4:5]
	v_mul_f32_e32 v45, 0x37800000, v44
	v_cndmask_b32_e32 v44, v44, v45, vcc
	v_cmp_class_f32_e32 vcc, v43, v204
	s_nop 1
	v_cndmask_b32_e32 v43, v44, v43, vcc
	v_div_scale_f32 v44, s[4:5], v43, v43, 1.0
	v_rcp_f32_e32 v45, v44
	s_mov_b32 s4, 0x17600000
	v_fma_f32 v54, -v44, v45, 1.0
	v_fmac_f32_e32 v45, v54, v45
	v_div_scale_f32 v54, vcc, 1.0, v43, 1.0
	v_mul_f32_e32 v55, v54, v45
	v_fma_f32 v56, -v44, v55, v54
	v_fmac_f32_e32 v55, v56, v45
	v_fma_f32 v44, -v44, v55, v54
	v_div_fmas_f32 v44, v44, v45, v55
	v_div_fixup_f32 v44, v44, v43, 1.0
	v_pk_mul_f32 v[0:1], v[0:1], v[44:45] op_sel_hi:[1,0]
	v_pk_mul_f32 v[2:3], v[2:3], v[44:45] op_sel_hi:[1,0]
	v_pk_fma_f32 v[0:1], v[26:27], v[0:1], v[34:35]
	v_pk_fma_f32 v[2:3], v[2:3], v[22:23], v[30:31]
	v_pk_fma_f32 v[0:1], v[42:43], v[4:5], v[0:1] op_sel_hi:[0,1,1]
	v_pk_mul_f32 v[4:5], v[40:41], v[44:45] op_sel_hi:[1,0]
	v_pk_fma_f32 v[2:3], v[42:43], v[6:7], v[2:3] op_sel_hi:[0,1,1]
	v_pk_fma_f32 v[4:5], v[28:29], v[4:5], v[36:37]
	v_pk_mul_f32 v[6:7], v[38:39], v[44:45] op_sel_hi:[1,0]
	v_pk_fma_f32 v[4:5], v[42:43], v[50:51], v[4:5] op_sel_hi:[0,1,1]
	v_pk_fma_f32 v[6:7], v[6:7], v[24:25], v[32:33]
	v_pk_mul_f32 v[0:1], v[0:1], v[8:9]
	v_pk_mul_f32 v[4:5], v[4:5], v[52:53]
	v_pk_fma_f32 v[6:7], v[42:43], v[46:47], v[6:7] op_sel_hi:[0,1,1]
	v_pk_mul_f32 v[2:3], v[2:3], v[10:11]
	v_pk_mul_f32 v[6:7], v[6:7], v[48:49]
	v_cvt_pk_bf16_f32 v0, v0, v1
	v_cvt_pk_bf16_f32 v1, v4, v5
	v_add_co_u32_e32 v4, vcc, s4, v20
	v_cvt_pk_bf16_f32 v2, v2, v3
	v_cvt_pk_bf16_f32 v3, v6, v7
	v_addc_co_u32_e32 v5, vcc, 0, v21, vcc
	global_store_dwordx4 v[4:5], v[0:3], off
	s_cbranch_scc1 .LBB0_832

; __device__ __forceinline__ void phase_final_norm(const Frame& F, const bf16* x, const float* gain, float* out) {
;     for (int m = F.gw; m < T; m += F.NGW) {
;         const v4u* xr = (const v4u*)(x + (size_t)m * D) + F.lane;
;         v4u v[4]; float s = 0.f;
; #pragma unroll
;         for (int j = 0; j < 4; ++j) v[j] = xr[64 * j];
; #pragma unroll
;         for (int j = 0; j < 4; ++j)
; #pragma unroll
;             for (int q = 0; q < 4; ++q) { const float a = bf_lo(v[j][q]), b = bf_hi(v[j][q]); s += a * a + b * b; }
;         const float rstd = 1.0f / sqrtf(wave_sum(s) * (1.0f / D) + 1e-6f);
.LBB0_1503:
	v_readlane_b32 s2, v254, 17
	s_cmp_ge_i32 s2, s74
	s_cselect_b64 s[0:1], -1, 0
	s_cmp_lt_i32 s2, s75
	s_cselect_b64 s[2:3], -1, 0
	s_and_b64 s[0:1], s[0:1], s[2:3]
	s_and_b64 vcc, exec, s[0:1]
	s_cbranch_vccz .LBB0_1507
	s_mov_b32 s6, 0
	v_mbcnt_lo_u32_b32 v0, -1, 0
	v_mbcnt_hi_u32_b32 v0, -1, v0
	v_readlane_b32 s0, v254, 5
	v_readlane_b32 s8, v254, 1
	v_readlane_b32 s2, v254, 6
	v_add_u32_e32 v0, s0, v0
	v_readlane_b32 s9, v254, 2
	s_load_dwordx2 s[0:1], s[8:9], 0xf8
	s_waitcnt lgkmcnt(0)
	v_readlane_b32 s3, v254, 7
	s_load_dword s2, s[2:3], 0x0
	v_readfirstlane_b32 s3, v0
	s_ashr_i32 s4, s3, 6
	v_readlane_b32 s7, v254, 0
	s_waitcnt lgkmcnt(0)
	s_mov_b32 s3, s2
	s_mov_b32 s5, s7
	s_lshl_b32 s2, s5, 3
	s_add_i32 s2, s2, s4
	s_load_dwordx2 s[4:5], s[8:9], 0xf0
	s_waitcnt lgkmcnt(0)
	s_load_dwordx2 s[8:9], s[8:9], 0xf0
	s_waitcnt lgkmcnt(0)
	s_cmp_gt_i32 s2, 0x9fff
	s_cbranch_scc1 .LBB0_1507
	s_ashr_i32 s7, s6, 31
	s_lshl_b32 s4, s3, 3
	s_lshl_b64 s[6:7], s[6:7], 3
	v_readlane_b32 s10, v254, 1
	v_readlane_b32 s11, v254, 2
	s_add_u32 s6, s10, s6
	s_addc_u32 s7, s11, s7
	s_load_dwordx2 s[6:7], s[6:7], 0xe8
	v_and_b32_e32 v2, 63, v0
	v_mov_b32_e32 v1, 0
	v_lshlrev_b32_e32 v0, 5, v2
	s_ashr_i32 s3, s2, 31
	s_waitcnt lgkmcnt(0)
	v_lshl_add_u64 v[8:9], s[6:7], 0, v[0:1]
	s_mov_b64 s[6:7], 0x1000
	v_lshl_add_u64 v[10:11], v[8:9], 0, s[6:7]
	s_mov_b64 s[6:7], 0x1800
	s_waitcnt vmcnt(0)
	v_lshl_add_u64 v[12:13], v[8:9], 0, s[6:7]
	s_lshl_b64 s[6:7], s[2:3], 12
	s_add_u32 s0, s0, s6
	v_lshlrev_b32_e32 v2, 4, v2
	v_mov_b32_e32 v3, v1
	s_addc_u32 s1, s1, s7
	v_lshl_add_u64 v[2:3], s[0:1], 0, v[2:3]
	s_mov_b64 s[0:1], 0x35600000
	s_ashr_i32 s5, s4, 31
	v_lshl_add_u64 v[14:15], v[2:3], 0, s[0:1]
	s_lshl_b64 s[6:7], s[4:5], 12
	s_lshl_b64 s[0:1], s[2:3], 13
	s_add_u32 s0, s8, s0
	s_addc_u32 s1, s9, s1
	v_lshl_add_u64 v[0:1], s[0:1], 0, v[0:1]
	s_mov_b64 s[0:1], 0x1810
	v_lshl_add_u64 v[16:17], v[0:1], 0, s[0:1]
	s_lshl_b64 s[8:9], s[4:5], 13
	v_mov_b32_e32 v18, 0x358637bd
	s_mov_b32 s3, 0xf800000
	v_mov_b32_e32 v19, 0x260
	s_movk_i32 s5, 0xf000
	global_load_dwordx4 v[96:99], v[8:9], off offset:16
	global_load_dwordx4 v[100:103], v[8:9], off
	global_load_dwordx4 v[104:107], v[8:9], off offset:2048
	global_load_dwordx4 v[108:111], v[8:9], off offset:2064
	global_load_dwordx4 v[112:115], v[10:11], off
	global_load_dwordx4 v[116:119], v[10:11], off offset:16
	global_load_dwordx4 v[120:123], v[12:13], off
	global_load_dwordx4 v[124:127], v[12:13], off offset:16
.LBB0_1506:
	global_load_dwordx4 v[20:23], v[14:15], off offset:3072
	global_load_dwordx4 v[24:27], v[14:15], off
	global_load_dwordx4 v[28:31], v[14:15], off offset:1024
	global_load_dwordx4 v[32:35], v[14:15], off offset:2048
	v_mbcnt_lo_u32_b32 v38, -1, 0
	v_mbcnt_hi_u32_b32 v38, -1, v38
	v_mbcnt_lo_u32_b32 v39, -1, 0
	v_mbcnt_hi_u32_b32 v39, -1, v39
	v_mbcnt_lo_u32_b32 v40, -1, 0
	v_mbcnt_hi_u32_b32 v40, -1, v40
	v_mbcnt_lo_u32_b32 v41, -1, 0
	v_mbcnt_hi_u32_b32 v41, -1, v41
	v_mbcnt_lo_u32_b32 v42, -1, 0
	v_mbcnt_hi_u32_b32 v42, -1, v42
	v_mbcnt_lo_u32_b32 v43, -1, 0
	v_mbcnt_hi_u32_b32 v43, -1, v43
	v_lshlrev_b32_e32 v40, 2, v40
	v_lshlrev_b32_e32 v41, 2, v41
	v_lshlrev_b32_e32 v42, 2, v42
	v_lshlrev_b32_e32 v43, 2, v43
	v_xor_b32_e32 v86, 16, v40
	v_xor_b32_e32 v87, 32, v41
	v_xor_b32_e32 v88, 64, v42
	v_xor_b32_e32 v89, 0x80, v43
	v_lshlrev_b32_e32 v38, 2, v38
	v_lshlrev_b32_e32 v39, 2, v39
	v_xor_b32_e32 v84, 4, v38
	v_xor_b32_e32 v85, 8, v39
	v_add_co_u32_e32 v36, vcc, s5, v16
	s_add_i32 s2, s2, s4
	s_nop 0
	v_addc_co_u32_e32 v37, vcc, -1, v17, vcc
	v_lshl_add_u64 v[14:15], v[14:15], 0, s[6:7]
	s_cmp_lt_i32 s2, 0xa000
	s_waitcnt vmcnt(3)
	v_lshlrev_b32_e32 v52, 16, v20
	s_waitcnt vmcnt(2)
	v_lshlrev_b32_e32 v40, 16, v26
	v_and_b32_e32 v41, 0xffff0000, v26
	v_lshlrev_b32_e32 v26, 16, v27
	v_and_b32_e32 v27, 0xffff0000, v27
	v_lshlrev_b32_e32 v42, 16, v24
	v_and_b32_e32 v43, 0xffff0000, v24
	v_lshlrev_b32_e32 v24, 16, v25
	v_and_b32_e32 v25, 0xffff0000, v25
	v_pk_mul_f32 v[58:59], v[26:27], v[26:27]
	v_pk_mul_f32 v[60:61], v[42:43], v[42:43]
	v_pk_mul_f32 v[62:63], v[24:25], v[24:25]
	v_pk_mul_f32 v[56:57], v[40:41], v[40:41]
	v_add_f32_e32 v58, v58, v59
	v_add_f32_e32 v59, v62, v63
	v_add_f32_e32 v60, v60, v61
	s_waitcnt vmcnt(1)
	v_lshlrev_b32_e32 v46, 16, v28
	v_and_b32_e32 v47, 0xffff0000, v28
	v_add_f32_e32 v56, v56, v57
	v_add_f32_e32 v59, v60, v59
	v_lshlrev_b32_e32 v28, 16, v29
	v_and_b32_e32 v29, 0xffff0000, v29
	v_pk_mul_f32 v[68:69], v[46:47], v[46:47]
	v_add_f32_e32 v56, v56, v59
	v_lshlrev_b32_e32 v44, 16, v30
	v_and_b32_e32 v45, 0xffff0000, v30
	v_pk_mul_f32 v[70:71], v[28:29], v[28:29]
	v_add_f32_e32 v57, v68, v69
	v_add_f32_e32 v56, v58, v56
	v_lshlrev_b32_e32 v30, 16, v31
	v_and_b32_e32 v31, 0xffff0000, v31
	v_pk_mul_f32 v[64:65], v[44:45], v[44:45]
	v_add_f32_e32 v61, v70, v71
	v_add_f32_e32 v56, v57, v56
	s_waitcnt vmcnt(0)
; __device__ __forceinline__ void phase_final_norm(const Frame& F, const bf16* x, const float* gain, float* out) {
;     ...
;             for (int q = 0; q < 4; ++q) { const float a = bf_lo(v[j][q]), b = bf_hi(v[j][q]); s += a * a + b * b; }
;         const float rstd = 1.0f / sqrtf(wave_sum(s) * (1.0f / D) + 1e-6f);
;         const f32x4* gr = (const f32x4*)gain + 2 * F.lane; f32x4* o = (f32x4*)(out + (size_t)m * D) + 2 * F.lane;
; #pragma unroll
;         for (int j = 0; j < 4; ++j) { const f32x4 g0 = gr[128 * j], g1 = gr[128 * j + 1]; const v4u w = v[j];
;             f32x4 o0, o1; o0.x = bf_lo(w.x) * rstd * g0.x; o0.y = bf_hi(w.x) * rstd * g0.y; o0.z = bf_lo(w.y) * rstd * g0.z; o0.w = bf_hi(w.y) * rstd * g0.w;
;             o1.x = bf_lo(w.z) * rstd * g1.x; o1.y = bf_hi(w.z) * rstd * g1.y; o1.z = bf_lo(w.w) * rstd * g1.z; o1.w = bf_hi(w.w) * rstd * g1.w;
;             o[128 * j] = o0; o[128 * j + 1] = o1; }
	v_lshlrev_b32_e32 v50, 16, v32
	v_and_b32_e32 v51, 0xffff0000, v32
	v_pk_mul_f32 v[66:67], v[30:31], v[30:31]
	v_add_f32_e32 v62, v64, v65
	v_add_f32_e32 v56, v61, v56
	v_lshlrev_b32_e32 v32, 16, v33
	v_and_b32_e32 v33, 0xffff0000, v33
	v_pk_mul_f32 v[76:77], v[50:51], v[50:51]
	v_add_f32_e32 v63, v66, v67
	v_add_f32_e32 v56, v62, v56
	v_lshlrev_b32_e32 v48, 16, v34
	v_and_b32_e32 v49, 0xffff0000, v34
	v_pk_mul_f32 v[78:79], v[32:33], v[32:33]
	v_add_f32_e32 v64, v76, v77
	v_add_f32_e32 v56, v63, v56
	v_lshlrev_b32_e32 v34, 16, v35
	v_and_b32_e32 v35, 0xffff0000, v35
	v_pk_mul_f32 v[72:73], v[48:49], v[48:49]
	v_add_f32_e32 v65, v78, v79
	v_add_f32_e32 v56, v64, v56
	v_and_b32_e32 v53, 0xffff0000, v20
	v_pk_mul_f32 v[74:75], v[34:35], v[34:35]
	v_add_f32_e32 v66, v72, v73
	v_add_f32_e32 v56, v65, v56
	v_lshlrev_b32_e32 v20, 16, v21
	v_and_b32_e32 v21, 0xffff0000, v21
	v_pk_mul_f32 v[80:81], v[52:53], v[52:53]
	v_add_f32_e32 v67, v74, v75
	v_add_f32_e32 v56, v66, v56
	v_lshlrev_b32_e32 v39, 16, v23
	v_lshlrev_b32_e32 v38, 16, v22
	v_and_b32_e32 v23, 0xffff0000, v23
	v_and_b32_e32 v22, 0xffff0000, v22
	v_pk_mul_f32 v[82:83], v[20:21], v[20:21]
	v_add_f32_e32 v68, v80, v81
	v_add_f32_e32 v56, v67, v56
	v_pk_mul_f32 v[54:55], v[22:23], v[22:23]
	v_add_f32_e32 v69, v82, v83
	v_add_f32_e32 v56, v68, v56
	v_pk_fma_f32 v[54:55], v[38:39], v[38:39], v[54:55]
	v_add_f32_e32 v56, v69, v56
	v_add_f32_e32 v54, v54, v56
	v_add_f32_e32 v54, v55, v54
	ds_bpermute_b32 v55, v84, v54
	s_waitcnt lgkmcnt(0)
	v_add_f32_e32 v54, v54, v55
	ds_bpermute_b32 v55, v85, v54
	s_waitcnt lgkmcnt(0)
	v_add_f32_e32 v54, v54, v55
	ds_bpermute_b32 v55, v86, v54
	s_waitcnt lgkmcnt(0)
	v_add_f32_e32 v54, v54, v55
	ds_bpermute_b32 v55, v87, v54
	s_waitcnt lgkmcnt(0)
	v_add_f32_e32 v54, v54, v55
	ds_bpermute_b32 v55, v88, v54
	s_waitcnt lgkmcnt(0)
	v_add_f32_e32 v54, v54, v55
	ds_bpermute_b32 v55, v89, v54
	s_waitcnt lgkmcnt(0)
	v_add_f32_e32 v54, v54, v55
	v_fmamk_f32 v54, v54, 0x3a000000, v18
	v_mul_f32_e32 v55, 0x4f800000, v54
	v_cmp_gt_f32_e32 vcc, s3, v54
	s_nop 1
	v_cndmask_b32_e32 v54, v54, v55, vcc
	v_sqrt_f32_e32 v55, v54
	s_nop 0
	v_add_u32_e32 v56, -1, v55
	v_add_u32_e32 v57, 1, v55
	v_fma_f32 v58, -v56, v55, v54
	v_fma_f32 v59, -v57, v55, v54
	v_cmp_ge_f32_e64 s[0:1], 0, v58
	s_nop 1
	v_cndmask_b32_e64 v55, v55, v56, s[0:1]
	v_cmp_lt_f32_e64 s[0:1], 0, v59
	s_nop 1
	v_cndmask_b32_e64 v55, v55, v57, s[0:1]
	v_mul_f32_e32 v56, 0x37800000, v55
	v_cndmask_b32_e32 v55, v55, v56, vcc
	v_cmp_class_f32_e32 vcc, v54, v19
	s_nop 1
	v_cndmask_b32_e32 v54, v55, v54, vcc
	v_div_scale_f32 v55, s[0:1], v54, v54, 1.0
	v_rcp_f32_e32 v57, v55
	v_div_scale_f32 v56, vcc, 1.0, v54, 1.0
	v_fma_f32 v58, -v55, v57, 1.0
	v_fmac_f32_e32 v57, v58, v57
	v_mul_f32_e32 v58, v56, v57
	v_fma_f32 v59, -v55, v58, v56
	v_fmac_f32_e32 v58, v59, v57
	v_fma_f32 v55, -v55, v58, v56
	v_div_fmas_f32 v55, v55, v57, v58
	v_div_fixup_f32 v54, v55, v54, 1.0
	v_pk_mul_f32 v[42:43], v[54:55], v[42:43] op_sel_hi:[0,1]
	v_pk_mul_f32 v[24:25], v[54:55], v[24:25] op_sel_hi:[0,1]
	v_pk_mul_f32 v[40:41], v[54:55], v[40:41] op_sel_hi:[0,1]
	v_pk_mul_f32 v[26:27], v[54:55], v[26:27] op_sel_hi:[0,1]
	s_waitcnt vmcnt(0)
	s_nop 1
	v_mov_b32_e32 v0, v96
	v_mov_b32_e32 v1, v97
	v_mov_b32_e32 v2, v98
	v_mov_b32_e32 v3, v99
	s_nop 1
	v_mov_b32_e32 v4, v100
	v_mov_b32_e32 v5, v101
	v_mov_b32_e32 v6, v102
	v_mov_b32_e32 v7, v103
	v_pk_mul_f32 v[6:7], v[6:7], v[24:25]
	v_pk_mul_f32 v[4:5], v[4:5], v[42:43]
	v_pk_mul_f32 v[2:3], v[2:3], v[26:27]
	v_pk_mul_f32 v[0:1], v[0:1], v[40:41]
	global_store_dwordx4 v[36:37], v[4:7], off offset:-2064
	global_store_dwordx4 v[36:37], v[0:3], off offset:-2048
	s_nop 1
	v_mov_b32_e32 v0, v104
	v_mov_b32_e32 v1, v105
	v_mov_b32_e32 v2, v106
	v_mov_b32_e32 v3, v107
	s_nop 0
	s_nop 1
	v_mov_b32_e32 v4, v108
	v_mov_b32_e32 v5, v109
	v_mov_b32_e32 v6, v110
	v_mov_b32_e32 v7, v111
	v_pk_mul_f32 v[24:25], v[54:55], v[28:29] op_sel_hi:[0,1]
	v_pk_mul_f32 v[26:27], v[54:55], v[46:47] op_sel_hi:[0,1]
	v_pk_mul_f32 v[28:29], v[54:55], v[30:31] op_sel_hi:[0,1]
	v_pk_mul_f32 v[30:31], v[54:55], v[44:45] op_sel_hi:[0,1]
	v_pk_mul_f32 v[20:21], v[54:55], v[20:21] op_sel_hi:[0,1]
	v_pk_mul_f32 v[0:1], v[0:1], v[26:27]
	v_pk_mul_f32 v[2:3], v[2:3], v[24:25]
	v_pk_mul_f32 v[4:5], v[4:5], v[30:31]
	v_pk_mul_f32 v[6:7], v[6:7], v[28:29]
	global_store_dwordx4 v[36:37], v[0:3], off offset:-16
	global_store_dwordx4 v[16:17], v[4:7], off offset:-4096
	s_nop 1
	v_mov_b32_e32 v0, v112
	v_mov_b32_e32 v1, v113
	v_mov_b32_e32 v2, v114
	v_mov_b32_e32 v3, v115
	s_nop 0
	s_nop 1
	v_mov_b32_e32 v4, v116
	v_mov_b32_e32 v5, v117
	v_mov_b32_e32 v6, v118
	v_mov_b32_e32 v7, v119
	v_pk_mul_f32 v[24:25], v[54:55], v[32:33] op_sel_hi:[0,1]
	v_pk_mul_f32 v[26:27], v[54:55], v[50:51] op_sel_hi:[0,1]
	v_pk_mul_f32 v[28:29], v[54:55], v[34:35] op_sel_hi:[0,1]
	v_pk_mul_f32 v[30:31], v[54:55], v[48:49] op_sel_hi:[0,1]
	v_pk_mul_f32 v[0:1], v[0:1], v[26:27]
	v_pk_mul_f32 v[2:3], v[2:3], v[24:25]
	v_pk_mul_f32 v[4:5], v[4:5], v[30:31]
	v_pk_mul_f32 v[6:7], v[6:7], v[28:29]
	global_store_dwordx4 v[16:17], v[0:3], off offset:-2064
	global_store_dwordx4 v[16:17], v[4:7], off offset:-2048
	s_nop 1
	v_mov_b32_e32 v0, v120
	v_mov_b32_e32 v1, v121
	v_mov_b32_e32 v2, v122
	v_mov_b32_e32 v3, v123
	s_nop 0
	s_nop 1
	v_mov_b32_e32 v4, v124
	v_mov_b32_e32 v5, v125
	v_mov_b32_e32 v6, v126
	v_mov_b32_e32 v7, v127
	v_mov_b32_e32 v24, v38
	v_mov_b32_e32 v25, v22
	v_mov_b32_e32 v22, v39
	v_pk_mul_f32 v[26:27], v[54:55], v[52:53] op_sel_hi:[0,1]
	v_pk_mul_f32 v[24:25], v[54:55], v[24:25] op_sel_hi:[0,1]
	v_pk_mul_f32 v[22:23], v[54:55], v[22:23] op_sel_hi:[0,1]
	v_pk_mul_f32 v[0:1], v[0:1], v[26:27]
	v_pk_mul_f32 v[2:3], v[2:3], v[20:21]
	v_pk_mul_f32 v[4:5], v[4:5], v[24:25]
	v_pk_mul_f32 v[6:7], v[6:7], v[22:23]
	global_store_dwordx4 v[16:17], v[0:3], off offset:-16
	global_store_dwordx4 v[16:17], v[4:7], off
	v_lshl_add_u64 v[16:17], v[16:17], 0, s[8:9]
	s_cbranch_scc1 .LBB0_1506
